# hand-written gate-merge GEMM epilogue: all gate/merged loads prefetched with counted vmcnt instead of one serialized load-wait per block
# speedup vs baseline: 1.0111x; 1.0111x over previous
; __device__ __forceinline__ unsigned cvt_pk_bf16(float lo, float hi) { f32x2e v = {lo, hi}; bf16x2e b = __builtin_convertvector(v, bf16x2e); return __builtin_bit_cast(unsigned, b); }
; __device__ __forceinline__ float bflo(unsigned w) { return __uint_as_float(w << 16); }
; __device__ __forceinline__ float bfhi(unsigned w) { return __uint_as_float(w & 0xffff0000u); }
; __device__ __forceinline__ float sigm(float x) { return 1.0f / (1.0f + __expf(-x)); }
; __device__ __forceinline__ float bflo(unsigned w) { return __uint_as_float(w << 16); }
; __device__ __forceinline__ float bfhi(unsigned w) { return __uint_as_float(w & 0xffff0000u); }
; __device__ __forceinline__ float sigm(float x) { return 1.0f / (1.0f + __expf(-x)); }
;     __device__ __forceinline__ void operator()(const f32x4 (&acc)[2][2][4][2], const Unit& u, int wr, int wc, int fr, int fq) const {
;         const int row0 = u.pm * BM + wr * 64 + fr, col0 = u.pn * BM + wc * 32 + 8 * fq;
; #pragma unroll
;         for (int ai = 0; ai < 2; ++ai)
; #pragma unroll
;             for (int m = 0; m < 4; ++m) { const size_t row = (size_t)(row0 + ai * HALF + m * 16);
; #pragma unroll
;                 for (int bj = 0; bj < 2; ++bj) { const f32x4 v0 = acc[ai][bj][m][0], v1 = acc[ai][bj][m][1];
;                     const u32x4 gw = *(const u32x4*)(G + row * ldg + col0 + bj * HALF);
;                     float r[8];
;                     r[0] = sigm(bflo(gw.x)) * v0[0]; r[1] = sigm(bfhi(gw.x)) * v0[1]; r[2] = sigm(bflo(gw.y)) * v0[2]; r[3] = sigm(bfhi(gw.y)) * v0[3];
;                     r[4] = sigm(bflo(gw.z)) * v1[0]; r[5] = sigm(bfhi(gw.z)) * v1[1]; r[6] = sigm(bflo(gw.w)) * v1[2]; r[7] = sigm(bfhi(gw.w)) * v1[3];
;                     bf16_t* op = O + row * ldo + col0 + bj * HALF;
;                     if (!first) { const u32x4 ow = *(const u32x4*)op;
;                         r[0] += bflo(ow.x); r[1] += bfhi(ow.x); r[2] += bflo(ow.y); r[3] += bfhi(ow.y); r[4] += bflo(ow.z); r[5] += bfhi(ow.z); r[6] += bflo(ow.w); r[7] += bfhi(ow.w); }
;                     u32x4 w; w.x = cvt_pk_bf16(r[0], r[1]); w.y = cvt_pk_bf16(r[2], r[3]); w.z = cvt_pk_bf16(r[4], r[5]); w.w = cvt_pk_bf16(r[6], r[7]);
;                     *(u32x4*)op = w; } }
.LBB0_1136:
	v_lshl_or_b32 v144, s25, 8, v154
	v_lshl_add_u32 v146, s81, 8, v152
	v_ashrrev_i32_e32 v145, 31, v144
	v_mov_b64_e32 v[130:131], s[14:15]
	v_mov_b32_e32 v147, 0
	v_mad_i64_i32 v[130:131], vcc, v146, s29, v[130:131]
	v_lshlrev_b64 v[144:145], 1, v[144:145]
	v_lshlrev_b64 v[132:133], 11, v[146:147]
	v_lshl_add_u64 v[130:131], v[130:131], 0, v[144:145]
	v_lshl_add_u64 v[132:133], s[16:17], 0, v[132:133]
	s_mov_b32 s30, 0x8000
	v_lshl_add_u64 v[132:133], v[132:133], 0, v[144:145]
	s_lshl_b32 s31, s29, 4
	s_andn2_b64 vcc, exec, s[10:11]
	s_cbranch_vccnz .Lg5_epi_first
	global_load_dwordx4 v[148:151], v[130:131], off
	global_load_dwordx4 v[202:205], v[132:133], off
	global_load_dwordx4 v[156:159], v[130:131], off offset:256
	global_load_dwordx4 v[206:209], v[132:133], off offset:256
	v_mad_u64_u32 v[146:147], vcc, s31, 1, v[130:131]
	global_load_dwordx4 v[160:163], v[146:147], off
	v_mad_u64_u32 v[144:145], vcc, s30, 1, v[132:133]
	global_load_dwordx4 v[210:213], v[144:145], off
	v_mad_u64_u32 v[146:147], vcc, s31, 1, v[130:131]
	global_load_dwordx4 v[164:167], v[146:147], off offset:256
	v_mad_u64_u32 v[144:145], vcc, s30, 1, v[132:133]
	global_load_dwordx4 v[214:217], v[144:145], off offset:256
	v_mad_u64_u32 v[146:147], vcc, s31, 2, v[130:131]
	global_load_dwordx4 v[168:171], v[146:147], off
	v_mad_u64_u32 v[144:145], vcc, s30, 2, v[132:133]
	global_load_dwordx4 v[218:221], v[144:145], off
	v_mad_u64_u32 v[146:147], vcc, s31, 2, v[130:131]
	global_load_dwordx4 v[172:175], v[146:147], off offset:256
	v_mad_u64_u32 v[144:145], vcc, s30, 2, v[132:133]
	global_load_dwordx4 v[222:225], v[144:145], off offset:256
	v_mad_u64_u32 v[146:147], vcc, s31, 3, v[130:131]
	global_load_dwordx4 v[176:179], v[146:147], off
	v_mad_u64_u32 v[144:145], vcc, s30, 3, v[132:133]
	global_load_dwordx4 v[226:229], v[144:145], off
	v_mad_u64_u32 v[146:147], vcc, s31, 3, v[130:131]
	global_load_dwordx4 v[198:201], v[146:147], off offset:256
	v_mad_u64_u32 v[144:145], vcc, s30, 3, v[132:133]
	global_load_dwordx4 v[248:251], v[144:145], off offset:256
	s_waitcnt vmcnt(14)
	v_lshlrev_b32_e32 v144, 16, v148
	v_and_b32_e32 v145, 0xffff0000, v148
	v_lshlrev_b32_e32 v146, 16, v149
	v_and_b32_e32 v147, 0xffff0000, v149
	v_mul_f32_e32 v144, 0xbfb8aa3b, v144
	v_mul_f32_e32 v145, 0xbfb8aa3b, v145
	v_mul_f32_e32 v146, 0xbfb8aa3b, v146
	v_mul_f32_e32 v147, 0xbfb8aa3b, v147
	v_exp_f32_e32 v144, v144
	v_exp_f32_e32 v145, v145
	v_exp_f32_e32 v146, v146
	v_exp_f32_e32 v147, v147
	v_pk_add_f32 v[144:145], v[144:145], 1.0 op_sel_hi:[1,0]
	v_pk_add_f32 v[146:147], v[146:147], 1.0 op_sel_hi:[1,0]
	v_rcp_f32_e32 v144, v144
	v_rcp_f32_e32 v145, v145
	v_rcp_f32_e32 v146, v146
	v_rcp_f32_e32 v147, v147
	v_pk_mul_f32 v[126:127], v[126:127], v[144:145]
	v_pk_mul_f32 v[128:129], v[128:129], v[146:147]
	v_lshlrev_b32_e32 v144, 16, v150
	v_and_b32_e32 v145, 0xffff0000, v150
	v_lshlrev_b32_e32 v146, 16, v151
	v_and_b32_e32 v147, 0xffff0000, v151
	v_mul_f32_e32 v144, 0xbfb8aa3b, v144
	v_mul_f32_e32 v145, 0xbfb8aa3b, v145
	v_mul_f32_e32 v146, 0xbfb8aa3b, v146
	v_mul_f32_e32 v147, 0xbfb8aa3b, v147
	v_exp_f32_e32 v144, v144
	v_exp_f32_e32 v145, v145
	v_exp_f32_e32 v146, v146
	v_exp_f32_e32 v147, v147
	v_pk_add_f32 v[144:145], v[144:145], 1.0 op_sel_hi:[1,0]
	v_pk_add_f32 v[146:147], v[146:147], 1.0 op_sel_hi:[1,0]
	v_rcp_f32_e32 v144, v144
	v_rcp_f32_e32 v145, v145
	v_rcp_f32_e32 v146, v146
	v_rcp_f32_e32 v147, v147
	v_pk_mul_f32 v[122:123], v[122:123], v[144:145]
	v_pk_mul_f32 v[124:125], v[124:125], v[146:147]
	v_lshlrev_b32_e32 v144, 16, v202
	v_and_b32_e32 v145, 0xffff0000, v202
	v_lshlrev_b32_e32 v146, 16, v203
	v_and_b32_e32 v147, 0xffff0000, v203
	v_pk_add_f32 v[126:127], v[126:127], v[144:145]
	v_pk_add_f32 v[128:129], v[128:129], v[146:147]
	v_lshlrev_b32_e32 v144, 16, v204
	v_and_b32_e32 v145, 0xffff0000, v204
	v_lshlrev_b32_e32 v146, 16, v205
	v_and_b32_e32 v147, 0xffff0000, v205
	v_pk_add_f32 v[122:123], v[122:123], v[144:145]
	v_pk_add_f32 v[124:125], v[124:125], v[146:147]
	v_cvt_pk_bf16_f32 v148, v126, v127
	v_cvt_pk_bf16_f32 v149, v128, v129
	v_cvt_pk_bf16_f32 v150, v122, v123
	v_cvt_pk_bf16_f32 v151, v124, v125
	s_nop 0
	global_store_dwordx4 v[132:133], v[148:151], off
	v_mad_u64_u32 v[146:147], vcc, s31, 8, v[130:131]
	global_load_dwordx4 v[148:151], v[146:147], off
	v_mad_u64_u32 v[144:145], vcc, s30, 8, v[132:133]
	global_load_dwordx4 v[202:205], v[144:145], off
	s_waitcnt vmcnt(15)
	v_lshlrev_b32_e32 v144, 16, v156
	v_and_b32_e32 v145, 0xffff0000, v156
	v_lshlrev_b32_e32 v146, 16, v157
	v_and_b32_e32 v147, 0xffff0000, v157
	v_mul_f32_e32 v144, 0xbfb8aa3b, v144
	v_mul_f32_e32 v145, 0xbfb8aa3b, v145
	v_mul_f32_e32 v146, 0xbfb8aa3b, v146
	v_mul_f32_e32 v147, 0xbfb8aa3b, v147
	v_exp_f32_e32 v144, v144
	v_exp_f32_e32 v145, v145
	v_exp_f32_e32 v146, v146
	v_exp_f32_e32 v147, v147
	v_pk_add_f32 v[144:145], v[144:145], 1.0 op_sel_hi:[1,0]
	v_pk_add_f32 v[146:147], v[146:147], 1.0 op_sel_hi:[1,0]
	v_rcp_f32_e32 v144, v144
	v_rcp_f32_e32 v145, v145
	v_rcp_f32_e32 v146, v146
	v_rcp_f32_e32 v147, v147
	v_pk_mul_f32 v[118:119], v[118:119], v[144:145]
	v_pk_mul_f32 v[120:121], v[120:121], v[146:147]
	v_lshlrev_b32_e32 v144, 16, v158
	v_and_b32_e32 v145, 0xffff0000, v158
	v_lshlrev_b32_e32 v146, 16, v159
	v_and_b32_e32 v147, 0xffff0000, v159
	v_mul_f32_e32 v144, 0xbfb8aa3b, v144
	v_mul_f32_e32 v145, 0xbfb8aa3b, v145
	v_mul_f32_e32 v146, 0xbfb8aa3b, v146
	v_mul_f32_e32 v147, 0xbfb8aa3b, v147
	v_exp_f32_e32 v144, v144
	v_exp_f32_e32 v145, v145
	v_exp_f32_e32 v146, v146
	v_exp_f32_e32 v147, v147
	v_pk_add_f32 v[144:145], v[144:145], 1.0 op_sel_hi:[1,0]
	v_pk_add_f32 v[146:147], v[146:147], 1.0 op_sel_hi:[1,0]
	v_rcp_f32_e32 v144, v144
	v_rcp_f32_e32 v145, v145
	v_rcp_f32_e32 v146, v146
	v_rcp_f32_e32 v147, v147
	v_pk_mul_f32 v[114:115], v[114:115], v[144:145]
	v_pk_mul_f32 v[116:117], v[116:117], v[146:147]
	v_lshlrev_b32_e32 v144, 16, v206
	v_and_b32_e32 v145, 0xffff0000, v206
	v_lshlrev_b32_e32 v146, 16, v207
	v_and_b32_e32 v147, 0xffff0000, v207
	v_pk_add_f32 v[118:119], v[118:119], v[144:145]
	v_pk_add_f32 v[120:121], v[120:121], v[146:147]
	v_lshlrev_b32_e32 v144, 16, v208
	v_and_b32_e32 v145, 0xffff0000, v208
	v_lshlrev_b32_e32 v146, 16, v209
	v_and_b32_e32 v147, 0xffff0000, v209
	v_pk_add_f32 v[114:115], v[114:115], v[144:145]
	v_pk_add_f32 v[116:117], v[116:117], v[146:147]
	v_cvt_pk_bf16_f32 v156, v118, v119
	v_cvt_pk_bf16_f32 v157, v120, v121
	v_cvt_pk_bf16_f32 v158, v114, v115
	v_cvt_pk_bf16_f32 v159, v116, v117
	s_nop 0
	global_store_dwordx4 v[132:133], v[156:159], off offset:256
	v_mad_u64_u32 v[146:147], vcc, s31, 8, v[130:131]
	global_load_dwordx4 v[156:159], v[146:147], off offset:256
	v_mad_u64_u32 v[144:145], vcc, s30, 8, v[132:133]
	global_load_dwordx4 v[206:209], v[144:145], off offset:256
	s_waitcnt vmcnt(16)
; __device__ __forceinline__ unsigned cvt_pk_bf16(float lo, float hi) { f32x2e v = {lo, hi}; bf16x2e b = __builtin_convertvector(v, bf16x2e); return __builtin_bit_cast(unsigned, b); }
; __device__ __forceinline__ float bflo(unsigned w) { return __uint_as_float(w << 16); }
; __device__ __forceinline__ float bfhi(unsigned w) { return __uint_as_float(w & 0xffff0000u); }
; __device__ __forceinline__ float sigm(float x) { return 1.0f / (1.0f + __expf(-x)); }
; __device__ __forceinline__ float bflo(unsigned w) { return __uint_as_float(w << 16); }
; __device__ __forceinline__ float bfhi(unsigned w) { return __uint_as_float(w & 0xffff0000u); }
; __device__ __forceinline__ float sigm(float x) { return 1.0f / (1.0f + __expf(-x)); }
;     __device__ __forceinline__ void operator()(const f32x4 (&acc)[2][2][4][2], const Unit& u, int wr, int wc, int fr, int fq) const {
;     ...
;             for (int m = 0; m < 4; ++m) { const size_t row = (size_t)(row0 + ai * HALF + m * 16);
; #pragma unroll
;                 for (int bj = 0; bj < 2; ++bj) { const f32x4 v0 = acc[ai][bj][m][0], v1 = acc[ai][bj][m][1];
;                     const u32x4 gw = *(const u32x4*)(G + row * ldg + col0 + bj * HALF);
;                     float r[8];
;                     r[0] = sigm(bflo(gw.x)) * v0[0]; r[1] = sigm(bfhi(gw.x)) * v0[1]; r[2] = sigm(bflo(gw.y)) * v0[2]; r[3] = sigm(bfhi(gw.y)) * v0[3];
;                     r[4] = sigm(bflo(gw.z)) * v1[0]; r[5] = sigm(bfhi(gw.z)) * v1[1]; r[6] = sigm(bflo(gw.w)) * v1[2]; r[7] = sigm(bfhi(gw.w)) * v1[3];
;                     bf16_t* op = O + row * ldo + col0 + bj * HALF;
;                     if (!first) { const u32x4 ow = *(const u32x4*)op;
;                         r[0] += bflo(ow.x); r[1] += bfhi(ow.x); r[2] += bflo(ow.y); r[3] += bfhi(ow.y); r[4] += bflo(ow.z); r[5] += bfhi(ow.z); r[6] += bflo(ow.w); r[7] += bfhi(ow.w); }
;                     u32x4 w; w.x = cvt_pk_bf16(r[0], r[1]); w.y = cvt_pk_bf16(r[2], r[3]); w.z = cvt_pk_bf16(r[4], r[5]); w.w = cvt_pk_bf16(r[6], r[7]);
;                     *(u32x4*)op = w; } }
	v_lshlrev_b32_e32 v144, 16, v160
	v_and_b32_e32 v145, 0xffff0000, v160
	v_lshlrev_b32_e32 v146, 16, v161
	v_and_b32_e32 v147, 0xffff0000, v161
	v_mul_f32_e32 v144, 0xbfb8aa3b, v144
	v_mul_f32_e32 v145, 0xbfb8aa3b, v145
	v_mul_f32_e32 v146, 0xbfb8aa3b, v146
	v_mul_f32_e32 v147, 0xbfb8aa3b, v147
	v_exp_f32_e32 v144, v144
	v_exp_f32_e32 v145, v145
	v_exp_f32_e32 v146, v146
	v_exp_f32_e32 v147, v147
	v_pk_add_f32 v[144:145], v[144:145], 1.0 op_sel_hi:[1,0]
	v_pk_add_f32 v[146:147], v[146:147], 1.0 op_sel_hi:[1,0]
	v_rcp_f32_e32 v144, v144
	v_rcp_f32_e32 v145, v145
	v_rcp_f32_e32 v146, v146
	v_rcp_f32_e32 v147, v147
	v_pk_mul_f32 v[110:111], v[110:111], v[144:145]
	v_pk_mul_f32 v[112:113], v[112:113], v[146:147]
	v_lshlrev_b32_e32 v144, 16, v162
	v_and_b32_e32 v145, 0xffff0000, v162
	v_lshlrev_b32_e32 v146, 16, v163
	v_and_b32_e32 v147, 0xffff0000, v163
	v_mul_f32_e32 v144, 0xbfb8aa3b, v144
	v_mul_f32_e32 v145, 0xbfb8aa3b, v145
	v_mul_f32_e32 v146, 0xbfb8aa3b, v146
	v_mul_f32_e32 v147, 0xbfb8aa3b, v147
	v_exp_f32_e32 v144, v144
	v_exp_f32_e32 v145, v145
	v_exp_f32_e32 v146, v146
	v_exp_f32_e32 v147, v147
	v_pk_add_f32 v[144:145], v[144:145], 1.0 op_sel_hi:[1,0]
	v_pk_add_f32 v[146:147], v[146:147], 1.0 op_sel_hi:[1,0]
	v_rcp_f32_e32 v144, v144
	v_rcp_f32_e32 v145, v145
	v_rcp_f32_e32 v146, v146
	v_rcp_f32_e32 v147, v147
	v_pk_mul_f32 v[106:107], v[106:107], v[144:145]
	v_pk_mul_f32 v[108:109], v[108:109], v[146:147]
	v_lshlrev_b32_e32 v144, 16, v210
	v_and_b32_e32 v145, 0xffff0000, v210
	v_lshlrev_b32_e32 v146, 16, v211
	v_and_b32_e32 v147, 0xffff0000, v211
	v_pk_add_f32 v[110:111], v[110:111], v[144:145]
	v_pk_add_f32 v[112:113], v[112:113], v[146:147]
	v_lshlrev_b32_e32 v144, 16, v212
	v_and_b32_e32 v145, 0xffff0000, v212
	v_lshlrev_b32_e32 v146, 16, v213
	v_and_b32_e32 v147, 0xffff0000, v213
	v_pk_add_f32 v[106:107], v[106:107], v[144:145]
	v_pk_add_f32 v[108:109], v[108:109], v[146:147]
	v_cvt_pk_bf16_f32 v160, v110, v111
	v_cvt_pk_bf16_f32 v161, v112, v113
	v_cvt_pk_bf16_f32 v162, v106, v107
	v_cvt_pk_bf16_f32 v163, v108, v109
	v_mad_u64_u32 v[144:145], vcc, s30, 1, v[132:133]
	global_store_dwordx4 v[144:145], v[160:163], off
	v_mad_u64_u32 v[146:147], vcc, s31, 9, v[130:131]
	global_load_dwordx4 v[160:163], v[146:147], off
	v_mad_u64_u32 v[144:145], vcc, s30, 9, v[132:133]
	global_load_dwordx4 v[210:213], v[144:145], off
	s_waitcnt vmcnt(17)
	v_lshlrev_b32_e32 v144, 16, v164
	v_and_b32_e32 v145, 0xffff0000, v164
	v_lshlrev_b32_e32 v146, 16, v165
	v_and_b32_e32 v147, 0xffff0000, v165
	v_mul_f32_e32 v144, 0xbfb8aa3b, v144
	v_mul_f32_e32 v145, 0xbfb8aa3b, v145
	v_mul_f32_e32 v146, 0xbfb8aa3b, v146
	v_mul_f32_e32 v147, 0xbfb8aa3b, v147
	v_exp_f32_e32 v144, v144
	v_exp_f32_e32 v145, v145
	v_exp_f32_e32 v146, v146
	v_exp_f32_e32 v147, v147
	v_pk_add_f32 v[144:145], v[144:145], 1.0 op_sel_hi:[1,0]
	v_pk_add_f32 v[146:147], v[146:147], 1.0 op_sel_hi:[1,0]
	v_rcp_f32_e32 v144, v144
	v_rcp_f32_e32 v145, v145
	v_rcp_f32_e32 v146, v146
	v_rcp_f32_e32 v147, v147
	v_pk_mul_f32 v[102:103], v[102:103], v[144:145]
	v_pk_mul_f32 v[104:105], v[104:105], v[146:147]
	v_lshlrev_b32_e32 v144, 16, v166
	v_and_b32_e32 v145, 0xffff0000, v166
	v_lshlrev_b32_e32 v146, 16, v167
	v_and_b32_e32 v147, 0xffff0000, v167
	v_mul_f32_e32 v144, 0xbfb8aa3b, v144
	v_mul_f32_e32 v145, 0xbfb8aa3b, v145
	v_mul_f32_e32 v146, 0xbfb8aa3b, v146
	v_mul_f32_e32 v147, 0xbfb8aa3b, v147
	v_exp_f32_e32 v144, v144
	v_exp_f32_e32 v145, v145
	v_exp_f32_e32 v146, v146
	v_exp_f32_e32 v147, v147
	v_pk_add_f32 v[144:145], v[144:145], 1.0 op_sel_hi:[1,0]
	v_pk_add_f32 v[146:147], v[146:147], 1.0 op_sel_hi:[1,0]
	v_rcp_f32_e32 v144, v144
	v_rcp_f32_e32 v145, v145
	v_rcp_f32_e32 v146, v146
	v_rcp_f32_e32 v147, v147
	v_pk_mul_f32 v[98:99], v[98:99], v[144:145]
	v_pk_mul_f32 v[100:101], v[100:101], v[146:147]
	v_lshlrev_b32_e32 v144, 16, v214
	v_and_b32_e32 v145, 0xffff0000, v214
	v_lshlrev_b32_e32 v146, 16, v215
	v_and_b32_e32 v147, 0xffff0000, v215
	v_pk_add_f32 v[102:103], v[102:103], v[144:145]
	v_pk_add_f32 v[104:105], v[104:105], v[146:147]
	v_lshlrev_b32_e32 v144, 16, v216
	v_and_b32_e32 v145, 0xffff0000, v216
	v_lshlrev_b32_e32 v146, 16, v217
	v_and_b32_e32 v147, 0xffff0000, v217
	v_pk_add_f32 v[98:99], v[98:99], v[144:145]
	v_pk_add_f32 v[100:101], v[100:101], v[146:147]
	v_cvt_pk_bf16_f32 v164, v102, v103
	v_cvt_pk_bf16_f32 v165, v104, v105
	v_cvt_pk_bf16_f32 v166, v98, v99
	v_cvt_pk_bf16_f32 v167, v100, v101
	v_mad_u64_u32 v[144:145], vcc, s30, 1, v[132:133]
	global_store_dwordx4 v[144:145], v[164:167], off offset:256
	v_mad_u64_u32 v[146:147], vcc, s31, 9, v[130:131]
	global_load_dwordx4 v[164:167], v[146:147], off offset:256
	v_mad_u64_u32 v[144:145], vcc, s30, 9, v[132:133]
	global_load_dwordx4 v[214:217], v[144:145], off offset:256
	s_waitcnt vmcnt(18)
; __device__ __forceinline__ unsigned cvt_pk_bf16(float lo, float hi) { f32x2e v = {lo, hi}; bf16x2e b = __builtin_convertvector(v, bf16x2e); return __builtin_bit_cast(unsigned, b); }
; __device__ __forceinline__ float bflo(unsigned w) { return __uint_as_float(w << 16); }
; __device__ __forceinline__ float bfhi(unsigned w) { return __uint_as_float(w & 0xffff0000u); }
; __device__ __forceinline__ float sigm(float x) { return 1.0f / (1.0f + __expf(-x)); }
; __device__ __forceinline__ float bflo(unsigned w) { return __uint_as_float(w << 16); }
; __device__ __forceinline__ float bfhi(unsigned w) { return __uint_as_float(w & 0xffff0000u); }
; __device__ __forceinline__ float sigm(float x) { return 1.0f / (1.0f + __expf(-x)); }
;     __device__ __forceinline__ void operator()(const f32x4 (&acc)[2][2][4][2], const Unit& u, int wr, int wc, int fr, int fq) const {
;     ...
;             for (int m = 0; m < 4; ++m) { const size_t row = (size_t)(row0 + ai * HALF + m * 16);
; #pragma unroll
;                 for (int bj = 0; bj < 2; ++bj) { const f32x4 v0 = acc[ai][bj][m][0], v1 = acc[ai][bj][m][1];
;                     const u32x4 gw = *(const u32x4*)(G + row * ldg + col0 + bj * HALF);
;                     float r[8];
;                     r[0] = sigm(bflo(gw.x)) * v0[0]; r[1] = sigm(bfhi(gw.x)) * v0[1]; r[2] = sigm(bflo(gw.y)) * v0[2]; r[3] = sigm(bfhi(gw.y)) * v0[3];
;                     r[4] = sigm(bflo(gw.z)) * v1[0]; r[5] = sigm(bfhi(gw.z)) * v1[1]; r[6] = sigm(bflo(gw.w)) * v1[2]; r[7] = sigm(bfhi(gw.w)) * v1[3];
;                     bf16_t* op = O + row * ldo + col0 + bj * HALF;
;                     if (!first) { const u32x4 ow = *(const u32x4*)op;
;                         r[0] += bflo(ow.x); r[1] += bfhi(ow.x); r[2] += bflo(ow.y); r[3] += bfhi(ow.y); r[4] += bflo(ow.z); r[5] += bfhi(ow.z); r[6] += bflo(ow.w); r[7] += bfhi(ow.w); }
;                     u32x4 w; w.x = cvt_pk_bf16(r[0], r[1]); w.y = cvt_pk_bf16(r[2], r[3]); w.z = cvt_pk_bf16(r[4], r[5]); w.w = cvt_pk_bf16(r[6], r[7]);
;                     *(u32x4*)op = w; } }
	v_lshlrev_b32_e32 v144, 16, v168
	v_and_b32_e32 v145, 0xffff0000, v168
	v_lshlrev_b32_e32 v146, 16, v169
	v_and_b32_e32 v147, 0xffff0000, v169
	v_mul_f32_e32 v144, 0xbfb8aa3b, v144
	v_mul_f32_e32 v145, 0xbfb8aa3b, v145
	v_mul_f32_e32 v146, 0xbfb8aa3b, v146
	v_mul_f32_e32 v147, 0xbfb8aa3b, v147
	v_exp_f32_e32 v144, v144
	v_exp_f32_e32 v145, v145
	v_exp_f32_e32 v146, v146
	v_exp_f32_e32 v147, v147
	v_pk_add_f32 v[144:145], v[144:145], 1.0 op_sel_hi:[1,0]
	v_pk_add_f32 v[146:147], v[146:147], 1.0 op_sel_hi:[1,0]
	v_rcp_f32_e32 v144, v144
	v_rcp_f32_e32 v145, v145
	v_rcp_f32_e32 v146, v146
	v_rcp_f32_e32 v147, v147
	v_pk_mul_f32 v[94:95], v[94:95], v[144:145]
	v_pk_mul_f32 v[96:97], v[96:97], v[146:147]
	v_lshlrev_b32_e32 v144, 16, v170
	v_and_b32_e32 v145, 0xffff0000, v170
	v_lshlrev_b32_e32 v146, 16, v171
	v_and_b32_e32 v147, 0xffff0000, v171
	v_mul_f32_e32 v144, 0xbfb8aa3b, v144
	v_mul_f32_e32 v145, 0xbfb8aa3b, v145
	v_mul_f32_e32 v146, 0xbfb8aa3b, v146
	v_mul_f32_e32 v147, 0xbfb8aa3b, v147
	v_exp_f32_e32 v144, v144
	v_exp_f32_e32 v145, v145
	v_exp_f32_e32 v146, v146
	v_exp_f32_e32 v147, v147
	v_pk_add_f32 v[144:145], v[144:145], 1.0 op_sel_hi:[1,0]
	v_pk_add_f32 v[146:147], v[146:147], 1.0 op_sel_hi:[1,0]
	v_rcp_f32_e32 v144, v144
	v_rcp_f32_e32 v145, v145
	v_rcp_f32_e32 v146, v146
	v_rcp_f32_e32 v147, v147
	v_pk_mul_f32 v[90:91], v[90:91], v[144:145]
	v_pk_mul_f32 v[92:93], v[92:93], v[146:147]
	v_lshlrev_b32_e32 v144, 16, v218
	v_and_b32_e32 v145, 0xffff0000, v218
	v_lshlrev_b32_e32 v146, 16, v219
	v_and_b32_e32 v147, 0xffff0000, v219
	v_pk_add_f32 v[94:95], v[94:95], v[144:145]
	v_pk_add_f32 v[96:97], v[96:97], v[146:147]
	v_lshlrev_b32_e32 v144, 16, v220
	v_and_b32_e32 v145, 0xffff0000, v220
	v_lshlrev_b32_e32 v146, 16, v221
	v_and_b32_e32 v147, 0xffff0000, v221
	v_pk_add_f32 v[90:91], v[90:91], v[144:145]
	v_pk_add_f32 v[92:93], v[92:93], v[146:147]
	v_cvt_pk_bf16_f32 v168, v94, v95
	v_cvt_pk_bf16_f32 v169, v96, v97
	v_cvt_pk_bf16_f32 v170, v90, v91
	v_cvt_pk_bf16_f32 v171, v92, v93
	v_mad_u64_u32 v[144:145], vcc, s30, 2, v[132:133]
	global_store_dwordx4 v[144:145], v[168:171], off
	v_mad_u64_u32 v[146:147], vcc, s31, 10, v[130:131]
	global_load_dwordx4 v[168:171], v[146:147], off
	v_mad_u64_u32 v[144:145], vcc, s30, 10, v[132:133]
	global_load_dwordx4 v[218:221], v[144:145], off
	s_waitcnt vmcnt(19)
	v_lshlrev_b32_e32 v144, 16, v172
	v_and_b32_e32 v145, 0xffff0000, v172
	v_lshlrev_b32_e32 v146, 16, v173
	v_and_b32_e32 v147, 0xffff0000, v173
	v_mul_f32_e32 v144, 0xbfb8aa3b, v144
	v_mul_f32_e32 v145, 0xbfb8aa3b, v145
	v_mul_f32_e32 v146, 0xbfb8aa3b, v146
	v_mul_f32_e32 v147, 0xbfb8aa3b, v147
	v_exp_f32_e32 v144, v144
	v_exp_f32_e32 v145, v145
	v_exp_f32_e32 v146, v146
	v_exp_f32_e32 v147, v147
	v_pk_add_f32 v[144:145], v[144:145], 1.0 op_sel_hi:[1,0]
	v_pk_add_f32 v[146:147], v[146:147], 1.0 op_sel_hi:[1,0]
	v_rcp_f32_e32 v144, v144
	v_rcp_f32_e32 v145, v145
	v_rcp_f32_e32 v146, v146
	v_rcp_f32_e32 v147, v147
	v_pk_mul_f32 v[86:87], v[86:87], v[144:145]
	v_pk_mul_f32 v[88:89], v[88:89], v[146:147]
	v_lshlrev_b32_e32 v144, 16, v174
	v_and_b32_e32 v145, 0xffff0000, v174
	v_lshlrev_b32_e32 v146, 16, v175
	v_and_b32_e32 v147, 0xffff0000, v175
	v_mul_f32_e32 v144, 0xbfb8aa3b, v144
	v_mul_f32_e32 v145, 0xbfb8aa3b, v145
	v_mul_f32_e32 v146, 0xbfb8aa3b, v146
	v_mul_f32_e32 v147, 0xbfb8aa3b, v147
	v_exp_f32_e32 v144, v144
	v_exp_f32_e32 v145, v145
	v_exp_f32_e32 v146, v146
	v_exp_f32_e32 v147, v147
	v_pk_add_f32 v[144:145], v[144:145], 1.0 op_sel_hi:[1,0]
	v_pk_add_f32 v[146:147], v[146:147], 1.0 op_sel_hi:[1,0]
	v_rcp_f32_e32 v144, v144
	v_rcp_f32_e32 v145, v145
	v_rcp_f32_e32 v146, v146
	v_rcp_f32_e32 v147, v147
	v_pk_mul_f32 v[82:83], v[82:83], v[144:145]
	v_pk_mul_f32 v[84:85], v[84:85], v[146:147]
	v_lshlrev_b32_e32 v144, 16, v222
	v_and_b32_e32 v145, 0xffff0000, v222
	v_lshlrev_b32_e32 v146, 16, v223
	v_and_b32_e32 v147, 0xffff0000, v223
	v_pk_add_f32 v[86:87], v[86:87], v[144:145]
	v_pk_add_f32 v[88:89], v[88:89], v[146:147]
	v_lshlrev_b32_e32 v144, 16, v224
	v_and_b32_e32 v145, 0xffff0000, v224
	v_lshlrev_b32_e32 v146, 16, v225
	v_and_b32_e32 v147, 0xffff0000, v225
	v_pk_add_f32 v[82:83], v[82:83], v[144:145]
	v_pk_add_f32 v[84:85], v[84:85], v[146:147]
	v_cvt_pk_bf16_f32 v172, v86, v87
	v_cvt_pk_bf16_f32 v173, v88, v89
	v_cvt_pk_bf16_f32 v174, v82, v83
	v_cvt_pk_bf16_f32 v175, v84, v85
	v_mad_u64_u32 v[144:145], vcc, s30, 2, v[132:133]
	global_store_dwordx4 v[144:145], v[172:175], off offset:256
	v_mad_u64_u32 v[146:147], vcc, s31, 10, v[130:131]
	global_load_dwordx4 v[172:175], v[146:147], off offset:256
	v_mad_u64_u32 v[144:145], vcc, s30, 10, v[132:133]
	global_load_dwordx4 v[222:225], v[144:145], off offset:256
	s_waitcnt vmcnt(20)
; __device__ __forceinline__ unsigned cvt_pk_bf16(float lo, float hi) { f32x2e v = {lo, hi}; bf16x2e b = __builtin_convertvector(v, bf16x2e); return __builtin_bit_cast(unsigned, b); }
; __device__ __forceinline__ float bflo(unsigned w) { return __uint_as_float(w << 16); }
; __device__ __forceinline__ float bfhi(unsigned w) { return __uint_as_float(w & 0xffff0000u); }
; __device__ __forceinline__ float sigm(float x) { return 1.0f / (1.0f + __expf(-x)); }
; __device__ __forceinline__ float bflo(unsigned w) { return __uint_as_float(w << 16); }
; __device__ __forceinline__ float bfhi(unsigned w) { return __uint_as_float(w & 0xffff0000u); }
; __device__ __forceinline__ float sigm(float x) { return 1.0f / (1.0f + __expf(-x)); }
;     __device__ __forceinline__ void operator()(const f32x4 (&acc)[2][2][4][2], const Unit& u, int wr, int wc, int fr, int fq) const {
;     ...
;             for (int m = 0; m < 4; ++m) { const size_t row = (size_t)(row0 + ai * HALF + m * 16);
; #pragma unroll
;                 for (int bj = 0; bj < 2; ++bj) { const f32x4 v0 = acc[ai][bj][m][0], v1 = acc[ai][bj][m][1];
;                     const u32x4 gw = *(const u32x4*)(G + row * ldg + col0 + bj * HALF);
;                     float r[8];
;                     r[0] = sigm(bflo(gw.x)) * v0[0]; r[1] = sigm(bfhi(gw.x)) * v0[1]; r[2] = sigm(bflo(gw.y)) * v0[2]; r[3] = sigm(bfhi(gw.y)) * v0[3];
;                     r[4] = sigm(bflo(gw.z)) * v1[0]; r[5] = sigm(bfhi(gw.z)) * v1[1]; r[6] = sigm(bflo(gw.w)) * v1[2]; r[7] = sigm(bfhi(gw.w)) * v1[3];
;                     bf16_t* op = O + row * ldo + col0 + bj * HALF;
;                     if (!first) { const u32x4 ow = *(const u32x4*)op;
;                         r[0] += bflo(ow.x); r[1] += bfhi(ow.x); r[2] += bflo(ow.y); r[3] += bfhi(ow.y); r[4] += bflo(ow.z); r[5] += bfhi(ow.z); r[6] += bflo(ow.w); r[7] += bfhi(ow.w); }
;                     u32x4 w; w.x = cvt_pk_bf16(r[0], r[1]); w.y = cvt_pk_bf16(r[2], r[3]); w.z = cvt_pk_bf16(r[4], r[5]); w.w = cvt_pk_bf16(r[6], r[7]);
;                     *(u32x4*)op = w; } }
	v_lshlrev_b32_e32 v144, 16, v176
	v_and_b32_e32 v145, 0xffff0000, v176
	v_lshlrev_b32_e32 v146, 16, v177
	v_and_b32_e32 v147, 0xffff0000, v177
	v_mul_f32_e32 v144, 0xbfb8aa3b, v144
	v_mul_f32_e32 v145, 0xbfb8aa3b, v145
	v_mul_f32_e32 v146, 0xbfb8aa3b, v146
	v_mul_f32_e32 v147, 0xbfb8aa3b, v147
	v_exp_f32_e32 v144, v144
	v_exp_f32_e32 v145, v145
	v_exp_f32_e32 v146, v146
	v_exp_f32_e32 v147, v147
	v_pk_add_f32 v[144:145], v[144:145], 1.0 op_sel_hi:[1,0]
	v_pk_add_f32 v[146:147], v[146:147], 1.0 op_sel_hi:[1,0]
	v_rcp_f32_e32 v144, v144
	v_rcp_f32_e32 v145, v145
	v_rcp_f32_e32 v146, v146
	v_rcp_f32_e32 v147, v147
	v_pk_mul_f32 v[78:79], v[78:79], v[144:145]
	v_pk_mul_f32 v[80:81], v[80:81], v[146:147]
	v_lshlrev_b32_e32 v144, 16, v178
	v_and_b32_e32 v145, 0xffff0000, v178
	v_lshlrev_b32_e32 v146, 16, v179
	v_and_b32_e32 v147, 0xffff0000, v179
	v_mul_f32_e32 v144, 0xbfb8aa3b, v144
	v_mul_f32_e32 v145, 0xbfb8aa3b, v145
	v_mul_f32_e32 v146, 0xbfb8aa3b, v146
	v_mul_f32_e32 v147, 0xbfb8aa3b, v147
	v_exp_f32_e32 v144, v144
	v_exp_f32_e32 v145, v145
	v_exp_f32_e32 v146, v146
	v_exp_f32_e32 v147, v147
	v_pk_add_f32 v[144:145], v[144:145], 1.0 op_sel_hi:[1,0]
	v_pk_add_f32 v[146:147], v[146:147], 1.0 op_sel_hi:[1,0]
	v_rcp_f32_e32 v144, v144
	v_rcp_f32_e32 v145, v145
	v_rcp_f32_e32 v146, v146
	v_rcp_f32_e32 v147, v147
	v_pk_mul_f32 v[74:75], v[74:75], v[144:145]
	v_pk_mul_f32 v[76:77], v[76:77], v[146:147]
	v_lshlrev_b32_e32 v144, 16, v226
	v_and_b32_e32 v145, 0xffff0000, v226
	v_lshlrev_b32_e32 v146, 16, v227
	v_and_b32_e32 v147, 0xffff0000, v227
	v_pk_add_f32 v[78:79], v[78:79], v[144:145]
	v_pk_add_f32 v[80:81], v[80:81], v[146:147]
	v_lshlrev_b32_e32 v144, 16, v228
	v_and_b32_e32 v145, 0xffff0000, v228
	v_lshlrev_b32_e32 v146, 16, v229
	v_and_b32_e32 v147, 0xffff0000, v229
	v_pk_add_f32 v[74:75], v[74:75], v[144:145]
	v_pk_add_f32 v[76:77], v[76:77], v[146:147]
	v_cvt_pk_bf16_f32 v176, v78, v79
	v_cvt_pk_bf16_f32 v177, v80, v81
	v_cvt_pk_bf16_f32 v178, v74, v75
	v_cvt_pk_bf16_f32 v179, v76, v77
	v_mad_u64_u32 v[144:145], vcc, s30, 3, v[132:133]
	global_store_dwordx4 v[144:145], v[176:179], off
	v_mad_u64_u32 v[146:147], vcc, s31, 11, v[130:131]
	global_load_dwordx4 v[176:179], v[146:147], off
	v_mad_u64_u32 v[144:145], vcc, s30, 11, v[132:133]
	global_load_dwordx4 v[226:229], v[144:145], off
	s_waitcnt vmcnt(21)
	v_lshlrev_b32_e32 v144, 16, v198
	v_and_b32_e32 v145, 0xffff0000, v198
	v_lshlrev_b32_e32 v146, 16, v199
	v_and_b32_e32 v147, 0xffff0000, v199
	v_mul_f32_e32 v144, 0xbfb8aa3b, v144
	v_mul_f32_e32 v145, 0xbfb8aa3b, v145
	v_mul_f32_e32 v146, 0xbfb8aa3b, v146
	v_mul_f32_e32 v147, 0xbfb8aa3b, v147
	v_exp_f32_e32 v144, v144
	v_exp_f32_e32 v145, v145
	v_exp_f32_e32 v146, v146
	v_exp_f32_e32 v147, v147
	v_pk_add_f32 v[144:145], v[144:145], 1.0 op_sel_hi:[1,0]
	v_pk_add_f32 v[146:147], v[146:147], 1.0 op_sel_hi:[1,0]
	v_rcp_f32_e32 v144, v144
	v_rcp_f32_e32 v145, v145
	v_rcp_f32_e32 v146, v146
	v_rcp_f32_e32 v147, v147
	v_pk_mul_f32 v[70:71], v[70:71], v[144:145]
	v_pk_mul_f32 v[72:73], v[72:73], v[146:147]
	v_lshlrev_b32_e32 v144, 16, v200
	v_and_b32_e32 v145, 0xffff0000, v200
	v_lshlrev_b32_e32 v146, 16, v201
	v_and_b32_e32 v147, 0xffff0000, v201
	v_mul_f32_e32 v144, 0xbfb8aa3b, v144
	v_mul_f32_e32 v145, 0xbfb8aa3b, v145
	v_mul_f32_e32 v146, 0xbfb8aa3b, v146
	v_mul_f32_e32 v147, 0xbfb8aa3b, v147
	v_exp_f32_e32 v144, v144
	v_exp_f32_e32 v145, v145
	v_exp_f32_e32 v146, v146
	v_exp_f32_e32 v147, v147
	v_pk_add_f32 v[144:145], v[144:145], 1.0 op_sel_hi:[1,0]
	v_pk_add_f32 v[146:147], v[146:147], 1.0 op_sel_hi:[1,0]
	v_rcp_f32_e32 v144, v144
	v_rcp_f32_e32 v145, v145
	v_rcp_f32_e32 v146, v146
	v_rcp_f32_e32 v147, v147
	v_pk_mul_f32 v[66:67], v[66:67], v[144:145]
	v_pk_mul_f32 v[68:69], v[68:69], v[146:147]
	v_lshlrev_b32_e32 v144, 16, v248
	v_and_b32_e32 v145, 0xffff0000, v248
	v_lshlrev_b32_e32 v146, 16, v249
	v_and_b32_e32 v147, 0xffff0000, v249
	v_pk_add_f32 v[70:71], v[70:71], v[144:145]
	v_pk_add_f32 v[72:73], v[72:73], v[146:147]
	v_lshlrev_b32_e32 v144, 16, v250
	v_and_b32_e32 v145, 0xffff0000, v250
	v_lshlrev_b32_e32 v146, 16, v251
	v_and_b32_e32 v147, 0xffff0000, v251
	v_pk_add_f32 v[66:67], v[66:67], v[144:145]
	v_pk_add_f32 v[68:69], v[68:69], v[146:147]
	v_cvt_pk_bf16_f32 v198, v70, v71
	v_cvt_pk_bf16_f32 v199, v72, v73
	v_cvt_pk_bf16_f32 v200, v66, v67
	v_cvt_pk_bf16_f32 v201, v68, v69
	v_mad_u64_u32 v[144:145], vcc, s30, 3, v[132:133]
	global_store_dwordx4 v[144:145], v[198:201], off offset:256
	v_mad_u64_u32 v[146:147], vcc, s31, 11, v[130:131]
	global_load_dwordx4 v[198:201], v[146:147], off offset:256
	v_mad_u64_u32 v[144:145], vcc, s30, 11, v[132:133]
	global_load_dwordx4 v[248:251], v[144:145], off offset:256
	s_waitcnt vmcnt(21)
; __device__ __forceinline__ unsigned cvt_pk_bf16(float lo, float hi) { f32x2e v = {lo, hi}; bf16x2e b = __builtin_convertvector(v, bf16x2e); return __builtin_bit_cast(unsigned, b); }
; __device__ __forceinline__ float bflo(unsigned w) { return __uint_as_float(w << 16); }
; __device__ __forceinline__ float bfhi(unsigned w) { return __uint_as_float(w & 0xffff0000u); }
; __device__ __forceinline__ float sigm(float x) { return 1.0f / (1.0f + __expf(-x)); }
; __device__ __forceinline__ float bflo(unsigned w) { return __uint_as_float(w << 16); }
; __device__ __forceinline__ float bfhi(unsigned w) { return __uint_as_float(w & 0xffff0000u); }
; __device__ __forceinline__ float sigm(float x) { return 1.0f / (1.0f + __expf(-x)); }
;     __device__ __forceinline__ void operator()(const f32x4 (&acc)[2][2][4][2], const Unit& u, int wr, int wc, int fr, int fq) const {
;     ...
;             for (int m = 0; m < 4; ++m) { const size_t row = (size_t)(row0 + ai * HALF + m * 16);
; #pragma unroll
;                 for (int bj = 0; bj < 2; ++bj) { const f32x4 v0 = acc[ai][bj][m][0], v1 = acc[ai][bj][m][1];
;                     const u32x4 gw = *(const u32x4*)(G + row * ldg + col0 + bj * HALF);
;                     float r[8];
;                     r[0] = sigm(bflo(gw.x)) * v0[0]; r[1] = sigm(bfhi(gw.x)) * v0[1]; r[2] = sigm(bflo(gw.y)) * v0[2]; r[3] = sigm(bfhi(gw.y)) * v0[3];
;                     r[4] = sigm(bflo(gw.z)) * v1[0]; r[5] = sigm(bfhi(gw.z)) * v1[1]; r[6] = sigm(bflo(gw.w)) * v1[2]; r[7] = sigm(bfhi(gw.w)) * v1[3];
;                     bf16_t* op = O + row * ldo + col0 + bj * HALF;
;                     if (!first) { const u32x4 ow = *(const u32x4*)op;
;                         r[0] += bflo(ow.x); r[1] += bfhi(ow.x); r[2] += bflo(ow.y); r[3] += bfhi(ow.y); r[4] += bflo(ow.z); r[5] += bfhi(ow.z); r[6] += bflo(ow.w); r[7] += bfhi(ow.w); }
;                     u32x4 w; w.x = cvt_pk_bf16(r[0], r[1]); w.y = cvt_pk_bf16(r[2], r[3]); w.z = cvt_pk_bf16(r[4], r[5]); w.w = cvt_pk_bf16(r[6], r[7]);
;                     *(u32x4*)op = w; } }
	v_lshlrev_b32_e32 v144, 16, v148
	v_and_b32_e32 v145, 0xffff0000, v148
	v_lshlrev_b32_e32 v146, 16, v149
	v_and_b32_e32 v147, 0xffff0000, v149
	v_mul_f32_e32 v144, 0xbfb8aa3b, v144
	v_mul_f32_e32 v145, 0xbfb8aa3b, v145
	v_mul_f32_e32 v146, 0xbfb8aa3b, v146
	v_mul_f32_e32 v147, 0xbfb8aa3b, v147
	v_exp_f32_e32 v144, v144
	v_exp_f32_e32 v145, v145
	v_exp_f32_e32 v146, v146
	v_exp_f32_e32 v147, v147
	v_pk_add_f32 v[144:145], v[144:145], 1.0 op_sel_hi:[1,0]
	v_pk_add_f32 v[146:147], v[146:147], 1.0 op_sel_hi:[1,0]
	v_rcp_f32_e32 v144, v144
	v_rcp_f32_e32 v145, v145
	v_rcp_f32_e32 v146, v146
	v_rcp_f32_e32 v147, v147
	v_pk_mul_f32 v[62:63], v[62:63], v[144:145]
	v_pk_mul_f32 v[64:65], v[64:65], v[146:147]
	v_lshlrev_b32_e32 v144, 16, v150
	v_and_b32_e32 v145, 0xffff0000, v150
	v_lshlrev_b32_e32 v146, 16, v151
	v_and_b32_e32 v147, 0xffff0000, v151
	v_mul_f32_e32 v144, 0xbfb8aa3b, v144
	v_mul_f32_e32 v145, 0xbfb8aa3b, v145
	v_mul_f32_e32 v146, 0xbfb8aa3b, v146
	v_mul_f32_e32 v147, 0xbfb8aa3b, v147
	v_exp_f32_e32 v144, v144
	v_exp_f32_e32 v145, v145
	v_exp_f32_e32 v146, v146
	v_exp_f32_e32 v147, v147
	v_pk_add_f32 v[144:145], v[144:145], 1.0 op_sel_hi:[1,0]
	v_pk_add_f32 v[146:147], v[146:147], 1.0 op_sel_hi:[1,0]
	v_rcp_f32_e32 v144, v144
	v_rcp_f32_e32 v145, v145
	v_rcp_f32_e32 v146, v146
	v_rcp_f32_e32 v147, v147
	v_pk_mul_f32 v[58:59], v[58:59], v[144:145]
	v_pk_mul_f32 v[60:61], v[60:61], v[146:147]
	v_lshlrev_b32_e32 v144, 16, v202
	v_and_b32_e32 v145, 0xffff0000, v202
	v_lshlrev_b32_e32 v146, 16, v203
	v_and_b32_e32 v147, 0xffff0000, v203
	v_pk_add_f32 v[62:63], v[62:63], v[144:145]
	v_pk_add_f32 v[64:65], v[64:65], v[146:147]
	v_lshlrev_b32_e32 v144, 16, v204
	v_and_b32_e32 v145, 0xffff0000, v204
	v_lshlrev_b32_e32 v146, 16, v205
	v_and_b32_e32 v147, 0xffff0000, v205
	v_pk_add_f32 v[58:59], v[58:59], v[144:145]
	v_pk_add_f32 v[60:61], v[60:61], v[146:147]
	v_cvt_pk_bf16_f32 v148, v62, v63
	v_cvt_pk_bf16_f32 v149, v64, v65
	v_cvt_pk_bf16_f32 v150, v58, v59
	v_cvt_pk_bf16_f32 v151, v60, v61
	v_mad_u64_u32 v[144:145], vcc, s30, 8, v[132:133]
	global_store_dwordx4 v[144:145], v[148:151], off
	s_waitcnt vmcnt(19)
	v_lshlrev_b32_e32 v144, 16, v156
	v_and_b32_e32 v145, 0xffff0000, v156
	v_lshlrev_b32_e32 v146, 16, v157
	v_and_b32_e32 v147, 0xffff0000, v157
	v_mul_f32_e32 v144, 0xbfb8aa3b, v144
	v_mul_f32_e32 v145, 0xbfb8aa3b, v145
	v_mul_f32_e32 v146, 0xbfb8aa3b, v146
	v_mul_f32_e32 v147, 0xbfb8aa3b, v147
	v_exp_f32_e32 v144, v144
	v_exp_f32_e32 v145, v145
	v_exp_f32_e32 v146, v146
	v_exp_f32_e32 v147, v147
	v_pk_add_f32 v[144:145], v[144:145], 1.0 op_sel_hi:[1,0]
	v_pk_add_f32 v[146:147], v[146:147], 1.0 op_sel_hi:[1,0]
	v_rcp_f32_e32 v144, v144
	v_rcp_f32_e32 v145, v145
	v_rcp_f32_e32 v146, v146
	v_rcp_f32_e32 v147, v147
	v_pk_mul_f32 v[54:55], v[54:55], v[144:145]
	v_pk_mul_f32 v[56:57], v[56:57], v[146:147]
	v_lshlrev_b32_e32 v144, 16, v158
	v_and_b32_e32 v145, 0xffff0000, v158
	v_lshlrev_b32_e32 v146, 16, v159
	v_and_b32_e32 v147, 0xffff0000, v159
	v_mul_f32_e32 v144, 0xbfb8aa3b, v144
	v_mul_f32_e32 v145, 0xbfb8aa3b, v145
	v_mul_f32_e32 v146, 0xbfb8aa3b, v146
	v_mul_f32_e32 v147, 0xbfb8aa3b, v147
	v_exp_f32_e32 v144, v144
	v_exp_f32_e32 v145, v145
	v_exp_f32_e32 v146, v146
	v_exp_f32_e32 v147, v147
	v_pk_add_f32 v[144:145], v[144:145], 1.0 op_sel_hi:[1,0]
	v_pk_add_f32 v[146:147], v[146:147], 1.0 op_sel_hi:[1,0]
	v_rcp_f32_e32 v144, v144
	v_rcp_f32_e32 v145, v145
	v_rcp_f32_e32 v146, v146
	v_rcp_f32_e32 v147, v147
	v_pk_mul_f32 v[50:51], v[50:51], v[144:145]
	v_pk_mul_f32 v[52:53], v[52:53], v[146:147]
	v_lshlrev_b32_e32 v144, 16, v206
	v_and_b32_e32 v145, 0xffff0000, v206
	v_lshlrev_b32_e32 v146, 16, v207
	v_and_b32_e32 v147, 0xffff0000, v207
	v_pk_add_f32 v[54:55], v[54:55], v[144:145]
	v_pk_add_f32 v[56:57], v[56:57], v[146:147]
	v_lshlrev_b32_e32 v144, 16, v208
	v_and_b32_e32 v145, 0xffff0000, v208
	v_lshlrev_b32_e32 v146, 16, v209
	v_and_b32_e32 v147, 0xffff0000, v209
	v_pk_add_f32 v[50:51], v[50:51], v[144:145]
	v_pk_add_f32 v[52:53], v[52:53], v[146:147]
	v_cvt_pk_bf16_f32 v156, v54, v55
	v_cvt_pk_bf16_f32 v157, v56, v57
	v_cvt_pk_bf16_f32 v158, v50, v51
	v_cvt_pk_bf16_f32 v159, v52, v53
	v_mad_u64_u32 v[144:145], vcc, s30, 8, v[132:133]
	global_store_dwordx4 v[144:145], v[156:159], off offset:256
	s_waitcnt vmcnt(17)
	v_lshlrev_b32_e32 v144, 16, v160
	v_and_b32_e32 v145, 0xffff0000, v160
	v_lshlrev_b32_e32 v146, 16, v161
	v_and_b32_e32 v147, 0xffff0000, v161
	v_mul_f32_e32 v144, 0xbfb8aa3b, v144
	v_mul_f32_e32 v145, 0xbfb8aa3b, v145
	v_mul_f32_e32 v146, 0xbfb8aa3b, v146
	v_mul_f32_e32 v147, 0xbfb8aa3b, v147
	v_exp_f32_e32 v144, v144
	v_exp_f32_e32 v145, v145
	v_exp_f32_e32 v146, v146
	v_exp_f32_e32 v147, v147
	v_pk_add_f32 v[144:145], v[144:145], 1.0 op_sel_hi:[1,0]
	v_pk_add_f32 v[146:147], v[146:147], 1.0 op_sel_hi:[1,0]
	v_rcp_f32_e32 v144, v144
	v_rcp_f32_e32 v145, v145
	v_rcp_f32_e32 v146, v146
	v_rcp_f32_e32 v147, v147
	v_pk_mul_f32 v[46:47], v[46:47], v[144:145]
	v_pk_mul_f32 v[48:49], v[48:49], v[146:147]
	v_lshlrev_b32_e32 v144, 16, v162
	v_and_b32_e32 v145, 0xffff0000, v162
	v_lshlrev_b32_e32 v146, 16, v163
	v_and_b32_e32 v147, 0xffff0000, v163
	v_mul_f32_e32 v144, 0xbfb8aa3b, v144
	v_mul_f32_e32 v145, 0xbfb8aa3b, v145
	v_mul_f32_e32 v146, 0xbfb8aa3b, v146
	v_mul_f32_e32 v147, 0xbfb8aa3b, v147
	v_exp_f32_e32 v144, v144
	v_exp_f32_e32 v145, v145
	v_exp_f32_e32 v146, v146
	v_exp_f32_e32 v147, v147
	v_pk_add_f32 v[144:145], v[144:145], 1.0 op_sel_hi:[1,0]
	v_pk_add_f32 v[146:147], v[146:147], 1.0 op_sel_hi:[1,0]
	v_rcp_f32_e32 v144, v144
	v_rcp_f32_e32 v145, v145
	v_rcp_f32_e32 v146, v146
	v_rcp_f32_e32 v147, v147
	v_pk_mul_f32 v[42:43], v[42:43], v[144:145]
	v_pk_mul_f32 v[44:45], v[44:45], v[146:147]
	v_lshlrev_b32_e32 v144, 16, v210
	v_and_b32_e32 v145, 0xffff0000, v210
	v_lshlrev_b32_e32 v146, 16, v211
	v_and_b32_e32 v147, 0xffff0000, v211
	v_pk_add_f32 v[46:47], v[46:47], v[144:145]
	v_pk_add_f32 v[48:49], v[48:49], v[146:147]
	v_lshlrev_b32_e32 v144, 16, v212
	v_and_b32_e32 v145, 0xffff0000, v212
	v_lshlrev_b32_e32 v146, 16, v213
	v_and_b32_e32 v147, 0xffff0000, v213
	v_pk_add_f32 v[42:43], v[42:43], v[144:145]
	v_pk_add_f32 v[44:45], v[44:45], v[146:147]
	v_cvt_pk_bf16_f32 v160, v46, v47
	v_cvt_pk_bf16_f32 v161, v48, v49
	v_cvt_pk_bf16_f32 v162, v42, v43
	v_cvt_pk_bf16_f32 v163, v44, v45
	v_mad_u64_u32 v[144:145], vcc, s30, 9, v[132:133]
	global_store_dwordx4 v[144:145], v[160:163], off
	s_waitcnt vmcnt(15)
; __device__ __forceinline__ unsigned cvt_pk_bf16(float lo, float hi) { f32x2e v = {lo, hi}; bf16x2e b = __builtin_convertvector(v, bf16x2e); return __builtin_bit_cast(unsigned, b); }
; __device__ __forceinline__ float bflo(unsigned w) { return __uint_as_float(w << 16); }
; __device__ __forceinline__ float bfhi(unsigned w) { return __uint_as_float(w & 0xffff0000u); }
; __device__ __forceinline__ float sigm(float x) { return 1.0f / (1.0f + __expf(-x)); }
; __device__ __forceinline__ float bflo(unsigned w) { return __uint_as_float(w << 16); }
; __device__ __forceinline__ float bfhi(unsigned w) { return __uint_as_float(w & 0xffff0000u); }
; __device__ __forceinline__ float sigm(float x) { return 1.0f / (1.0f + __expf(-x)); }
;     __device__ __forceinline__ void operator()(const f32x4 (&acc)[2][2][4][2], const Unit& u, int wr, int wc, int fr, int fq) const {
;     ...
;             for (int m = 0; m < 4; ++m) { const size_t row = (size_t)(row0 + ai * HALF + m * 16);
; #pragma unroll
;                 for (int bj = 0; bj < 2; ++bj) { const f32x4 v0 = acc[ai][bj][m][0], v1 = acc[ai][bj][m][1];
;                     const u32x4 gw = *(const u32x4*)(G + row * ldg + col0 + bj * HALF);
;                     float r[8];
;                     r[0] = sigm(bflo(gw.x)) * v0[0]; r[1] = sigm(bfhi(gw.x)) * v0[1]; r[2] = sigm(bflo(gw.y)) * v0[2]; r[3] = sigm(bfhi(gw.y)) * v0[3];
;                     r[4] = sigm(bflo(gw.z)) * v1[0]; r[5] = sigm(bfhi(gw.z)) * v1[1]; r[6] = sigm(bflo(gw.w)) * v1[2]; r[7] = sigm(bfhi(gw.w)) * v1[3];
;                     bf16_t* op = O + row * ldo + col0 + bj * HALF;
;                     if (!first) { const u32x4 ow = *(const u32x4*)op;
;                         r[0] += bflo(ow.x); r[1] += bfhi(ow.x); r[2] += bflo(ow.y); r[3] += bfhi(ow.y); r[4] += bflo(ow.z); r[5] += bfhi(ow.z); r[6] += bflo(ow.w); r[7] += bfhi(ow.w); }
;                     u32x4 w; w.x = cvt_pk_bf16(r[0], r[1]); w.y = cvt_pk_bf16(r[2], r[3]); w.z = cvt_pk_bf16(r[4], r[5]); w.w = cvt_pk_bf16(r[6], r[7]);
;                     *(u32x4*)op = w; } }
	v_lshlrev_b32_e32 v144, 16, v164
	v_and_b32_e32 v145, 0xffff0000, v164
	v_lshlrev_b32_e32 v146, 16, v165
	v_and_b32_e32 v147, 0xffff0000, v165
	v_mul_f32_e32 v144, 0xbfb8aa3b, v144
	v_mul_f32_e32 v145, 0xbfb8aa3b, v145
	v_mul_f32_e32 v146, 0xbfb8aa3b, v146
	v_mul_f32_e32 v147, 0xbfb8aa3b, v147
	v_exp_f32_e32 v144, v144
	v_exp_f32_e32 v145, v145
	v_exp_f32_e32 v146, v146
	v_exp_f32_e32 v147, v147
	v_pk_add_f32 v[144:145], v[144:145], 1.0 op_sel_hi:[1,0]
	v_pk_add_f32 v[146:147], v[146:147], 1.0 op_sel_hi:[1,0]
	v_rcp_f32_e32 v144, v144
	v_rcp_f32_e32 v145, v145
	v_rcp_f32_e32 v146, v146
	v_rcp_f32_e32 v147, v147
	v_pk_mul_f32 v[38:39], v[38:39], v[144:145]
	v_pk_mul_f32 v[40:41], v[40:41], v[146:147]
	v_lshlrev_b32_e32 v144, 16, v166
	v_and_b32_e32 v145, 0xffff0000, v166
	v_lshlrev_b32_e32 v146, 16, v167
	v_and_b32_e32 v147, 0xffff0000, v167
	v_mul_f32_e32 v144, 0xbfb8aa3b, v144
	v_mul_f32_e32 v145, 0xbfb8aa3b, v145
	v_mul_f32_e32 v146, 0xbfb8aa3b, v146
	v_mul_f32_e32 v147, 0xbfb8aa3b, v147
	v_exp_f32_e32 v144, v144
	v_exp_f32_e32 v145, v145
	v_exp_f32_e32 v146, v146
	v_exp_f32_e32 v147, v147
	v_pk_add_f32 v[144:145], v[144:145], 1.0 op_sel_hi:[1,0]
	v_pk_add_f32 v[146:147], v[146:147], 1.0 op_sel_hi:[1,0]
	v_rcp_f32_e32 v144, v144
	v_rcp_f32_e32 v145, v145
	v_rcp_f32_e32 v146, v146
	v_rcp_f32_e32 v147, v147
	v_pk_mul_f32 v[34:35], v[34:35], v[144:145]
	v_pk_mul_f32 v[36:37], v[36:37], v[146:147]
	v_lshlrev_b32_e32 v144, 16, v214
	v_and_b32_e32 v145, 0xffff0000, v214
	v_lshlrev_b32_e32 v146, 16, v215
	v_and_b32_e32 v147, 0xffff0000, v215
	v_pk_add_f32 v[38:39], v[38:39], v[144:145]
	v_pk_add_f32 v[40:41], v[40:41], v[146:147]
	v_lshlrev_b32_e32 v144, 16, v216
	v_and_b32_e32 v145, 0xffff0000, v216
	v_lshlrev_b32_e32 v146, 16, v217
	v_and_b32_e32 v147, 0xffff0000, v217
	v_pk_add_f32 v[34:35], v[34:35], v[144:145]
	v_pk_add_f32 v[36:37], v[36:37], v[146:147]
	v_cvt_pk_bf16_f32 v164, v38, v39
	v_cvt_pk_bf16_f32 v165, v40, v41
	v_cvt_pk_bf16_f32 v166, v34, v35
	v_cvt_pk_bf16_f32 v167, v36, v37
	v_mad_u64_u32 v[144:145], vcc, s30, 9, v[132:133]
	global_store_dwordx4 v[144:145], v[164:167], off offset:256
	s_waitcnt vmcnt(13)
	v_lshlrev_b32_e32 v144, 16, v168
	v_and_b32_e32 v145, 0xffff0000, v168
	v_lshlrev_b32_e32 v146, 16, v169
	v_and_b32_e32 v147, 0xffff0000, v169
	v_mul_f32_e32 v144, 0xbfb8aa3b, v144
	v_mul_f32_e32 v145, 0xbfb8aa3b, v145
	v_mul_f32_e32 v146, 0xbfb8aa3b, v146
	v_mul_f32_e32 v147, 0xbfb8aa3b, v147
	v_exp_f32_e32 v144, v144
	v_exp_f32_e32 v145, v145
	v_exp_f32_e32 v146, v146
	v_exp_f32_e32 v147, v147
	v_pk_add_f32 v[144:145], v[144:145], 1.0 op_sel_hi:[1,0]
	v_pk_add_f32 v[146:147], v[146:147], 1.0 op_sel_hi:[1,0]
	v_rcp_f32_e32 v144, v144
	v_rcp_f32_e32 v145, v145
	v_rcp_f32_e32 v146, v146
	v_rcp_f32_e32 v147, v147
	v_pk_mul_f32 v[30:31], v[30:31], v[144:145]
	v_pk_mul_f32 v[32:33], v[32:33], v[146:147]
	v_lshlrev_b32_e32 v144, 16, v170
	v_and_b32_e32 v145, 0xffff0000, v170
	v_lshlrev_b32_e32 v146, 16, v171
	v_and_b32_e32 v147, 0xffff0000, v171
	v_mul_f32_e32 v144, 0xbfb8aa3b, v144
	v_mul_f32_e32 v145, 0xbfb8aa3b, v145
	v_mul_f32_e32 v146, 0xbfb8aa3b, v146
	v_mul_f32_e32 v147, 0xbfb8aa3b, v147
	v_exp_f32_e32 v144, v144
	v_exp_f32_e32 v145, v145
	v_exp_f32_e32 v146, v146
	v_exp_f32_e32 v147, v147
	v_pk_add_f32 v[144:145], v[144:145], 1.0 op_sel_hi:[1,0]
	v_pk_add_f32 v[146:147], v[146:147], 1.0 op_sel_hi:[1,0]
	v_rcp_f32_e32 v144, v144
	v_rcp_f32_e32 v145, v145
	v_rcp_f32_e32 v146, v146
	v_rcp_f32_e32 v147, v147
	v_pk_mul_f32 v[26:27], v[26:27], v[144:145]
	v_pk_mul_f32 v[28:29], v[28:29], v[146:147]
	v_lshlrev_b32_e32 v144, 16, v218
	v_and_b32_e32 v145, 0xffff0000, v218
	v_lshlrev_b32_e32 v146, 16, v219
	v_and_b32_e32 v147, 0xffff0000, v219
	v_pk_add_f32 v[30:31], v[30:31], v[144:145]
	v_pk_add_f32 v[32:33], v[32:33], v[146:147]
	v_lshlrev_b32_e32 v144, 16, v220
	v_and_b32_e32 v145, 0xffff0000, v220
	v_lshlrev_b32_e32 v146, 16, v221
	v_and_b32_e32 v147, 0xffff0000, v221
	v_pk_add_f32 v[26:27], v[26:27], v[144:145]
	v_pk_add_f32 v[28:29], v[28:29], v[146:147]
	v_cvt_pk_bf16_f32 v168, v30, v31
	v_cvt_pk_bf16_f32 v169, v32, v33
	v_cvt_pk_bf16_f32 v170, v26, v27
	v_cvt_pk_bf16_f32 v171, v28, v29
	v_mad_u64_u32 v[144:145], vcc, s30, 10, v[132:133]
	global_store_dwordx4 v[144:145], v[168:171], off
	s_waitcnt vmcnt(11)
	v_lshlrev_b32_e32 v144, 16, v172
	v_and_b32_e32 v145, 0xffff0000, v172
	v_lshlrev_b32_e32 v146, 16, v173
	v_and_b32_e32 v147, 0xffff0000, v173
	v_mul_f32_e32 v144, 0xbfb8aa3b, v144
	v_mul_f32_e32 v145, 0xbfb8aa3b, v145
	v_mul_f32_e32 v146, 0xbfb8aa3b, v146
	v_mul_f32_e32 v147, 0xbfb8aa3b, v147
	v_exp_f32_e32 v144, v144
	v_exp_f32_e32 v145, v145
	v_exp_f32_e32 v146, v146
	v_exp_f32_e32 v147, v147
	v_pk_add_f32 v[144:145], v[144:145], 1.0 op_sel_hi:[1,0]
	v_pk_add_f32 v[146:147], v[146:147], 1.0 op_sel_hi:[1,0]
	v_rcp_f32_e32 v144, v144
	v_rcp_f32_e32 v145, v145
	v_rcp_f32_e32 v146, v146
	v_rcp_f32_e32 v147, v147
	v_pk_mul_f32 v[22:23], v[22:23], v[144:145]
	v_pk_mul_f32 v[24:25], v[24:25], v[146:147]
	v_lshlrev_b32_e32 v144, 16, v174
	v_and_b32_e32 v145, 0xffff0000, v174
	v_lshlrev_b32_e32 v146, 16, v175
	v_and_b32_e32 v147, 0xffff0000, v175
	v_mul_f32_e32 v144, 0xbfb8aa3b, v144
	v_mul_f32_e32 v145, 0xbfb8aa3b, v145
	v_mul_f32_e32 v146, 0xbfb8aa3b, v146
	v_mul_f32_e32 v147, 0xbfb8aa3b, v147
	v_exp_f32_e32 v144, v144
	v_exp_f32_e32 v145, v145
	v_exp_f32_e32 v146, v146
	v_exp_f32_e32 v147, v147
	v_pk_add_f32 v[144:145], v[144:145], 1.0 op_sel_hi:[1,0]
	v_pk_add_f32 v[146:147], v[146:147], 1.0 op_sel_hi:[1,0]
	v_rcp_f32_e32 v144, v144
	v_rcp_f32_e32 v145, v145
	v_rcp_f32_e32 v146, v146
	v_rcp_f32_e32 v147, v147
	v_pk_mul_f32 v[18:19], v[18:19], v[144:145]
	v_pk_mul_f32 v[20:21], v[20:21], v[146:147]
	v_lshlrev_b32_e32 v144, 16, v222
	v_and_b32_e32 v145, 0xffff0000, v222
	v_lshlrev_b32_e32 v146, 16, v223
	v_and_b32_e32 v147, 0xffff0000, v223
	v_pk_add_f32 v[22:23], v[22:23], v[144:145]
	v_pk_add_f32 v[24:25], v[24:25], v[146:147]
	v_lshlrev_b32_e32 v144, 16, v224
	v_and_b32_e32 v145, 0xffff0000, v224
	v_lshlrev_b32_e32 v146, 16, v225
	v_and_b32_e32 v147, 0xffff0000, v225
	v_pk_add_f32 v[18:19], v[18:19], v[144:145]
	v_pk_add_f32 v[20:21], v[20:21], v[146:147]
	v_cvt_pk_bf16_f32 v172, v22, v23
	v_cvt_pk_bf16_f32 v173, v24, v25
	v_cvt_pk_bf16_f32 v174, v18, v19
	v_cvt_pk_bf16_f32 v175, v20, v21
	v_mad_u64_u32 v[144:145], vcc, s30, 10, v[132:133]
	global_store_dwordx4 v[144:145], v[172:175], off offset:256
	s_waitcnt vmcnt(9)
; __device__ __forceinline__ unsigned cvt_pk_bf16(float lo, float hi) { f32x2e v = {lo, hi}; bf16x2e b = __builtin_convertvector(v, bf16x2e); return __builtin_bit_cast(unsigned, b); }
; __device__ __forceinline__ float bflo(unsigned w) { return __uint_as_float(w << 16); }
; __device__ __forceinline__ float bfhi(unsigned w) { return __uint_as_float(w & 0xffff0000u); }
; __device__ __forceinline__ float sigm(float x) { return 1.0f / (1.0f + __expf(-x)); }
; __device__ __forceinline__ float bflo(unsigned w) { return __uint_as_float(w << 16); }
; __device__ __forceinline__ float bfhi(unsigned w) { return __uint_as_float(w & 0xffff0000u); }
; __device__ __forceinline__ float sigm(float x) { return 1.0f / (1.0f + __expf(-x)); }
;     __device__ __forceinline__ void operator()(const f32x4 (&acc)[2][2][4][2], const Unit& u, int wr, int wc, int fr, int fq) const {
;     ...
;             for (int m = 0; m < 4; ++m) { const size_t row = (size_t)(row0 + ai * HALF + m * 16);
; #pragma unroll
;                 for (int bj = 0; bj < 2; ++bj) { const f32x4 v0 = acc[ai][bj][m][0], v1 = acc[ai][bj][m][1];
;                     const u32x4 gw = *(const u32x4*)(G + row * ldg + col0 + bj * HALF);
;                     float r[8];
;                     r[0] = sigm(bflo(gw.x)) * v0[0]; r[1] = sigm(bfhi(gw.x)) * v0[1]; r[2] = sigm(bflo(gw.y)) * v0[2]; r[3] = sigm(bfhi(gw.y)) * v0[3];
;                     r[4] = sigm(bflo(gw.z)) * v1[0]; r[5] = sigm(bfhi(gw.z)) * v1[1]; r[6] = sigm(bflo(gw.w)) * v1[2]; r[7] = sigm(bfhi(gw.w)) * v1[3];
;                     bf16_t* op = O + row * ldo + col0 + bj * HALF;
;                     if (!first) { const u32x4 ow = *(const u32x4*)op;
;                         r[0] += bflo(ow.x); r[1] += bfhi(ow.x); r[2] += bflo(ow.y); r[3] += bfhi(ow.y); r[4] += bflo(ow.z); r[5] += bfhi(ow.z); r[6] += bflo(ow.w); r[7] += bfhi(ow.w); }
;                     u32x4 w; w.x = cvt_pk_bf16(r[0], r[1]); w.y = cvt_pk_bf16(r[2], r[3]); w.z = cvt_pk_bf16(r[4], r[5]); w.w = cvt_pk_bf16(r[6], r[7]);
;                     *(u32x4*)op = w; } }
	v_lshlrev_b32_e32 v144, 16, v176
	v_and_b32_e32 v145, 0xffff0000, v176
	v_lshlrev_b32_e32 v146, 16, v177
	v_and_b32_e32 v147, 0xffff0000, v177
	v_mul_f32_e32 v144, 0xbfb8aa3b, v144
	v_mul_f32_e32 v145, 0xbfb8aa3b, v145
	v_mul_f32_e32 v146, 0xbfb8aa3b, v146
	v_mul_f32_e32 v147, 0xbfb8aa3b, v147
	v_exp_f32_e32 v144, v144
	v_exp_f32_e32 v145, v145
	v_exp_f32_e32 v146, v146
	v_exp_f32_e32 v147, v147
	v_pk_add_f32 v[144:145], v[144:145], 1.0 op_sel_hi:[1,0]
	v_pk_add_f32 v[146:147], v[146:147], 1.0 op_sel_hi:[1,0]
	v_rcp_f32_e32 v144, v144
	v_rcp_f32_e32 v145, v145
	v_rcp_f32_e32 v146, v146
	v_rcp_f32_e32 v147, v147
	v_pk_mul_f32 v[14:15], v[14:15], v[144:145]
	v_pk_mul_f32 v[16:17], v[16:17], v[146:147]
	v_lshlrev_b32_e32 v144, 16, v178
	v_and_b32_e32 v145, 0xffff0000, v178
	v_lshlrev_b32_e32 v146, 16, v179
	v_and_b32_e32 v147, 0xffff0000, v179
	v_mul_f32_e32 v144, 0xbfb8aa3b, v144
	v_mul_f32_e32 v145, 0xbfb8aa3b, v145
	v_mul_f32_e32 v146, 0xbfb8aa3b, v146
	v_mul_f32_e32 v147, 0xbfb8aa3b, v147
	v_exp_f32_e32 v144, v144
	v_exp_f32_e32 v145, v145
	v_exp_f32_e32 v146, v146
	v_exp_f32_e32 v147, v147
	v_pk_add_f32 v[144:145], v[144:145], 1.0 op_sel_hi:[1,0]
	v_pk_add_f32 v[146:147], v[146:147], 1.0 op_sel_hi:[1,0]
	v_rcp_f32_e32 v144, v144
	v_rcp_f32_e32 v145, v145
	v_rcp_f32_e32 v146, v146
	v_rcp_f32_e32 v147, v147
	v_pk_mul_f32 v[10:11], v[10:11], v[144:145]
	v_pk_mul_f32 v[12:13], v[12:13], v[146:147]
	v_lshlrev_b32_e32 v144, 16, v226
	v_and_b32_e32 v145, 0xffff0000, v226
	v_lshlrev_b32_e32 v146, 16, v227
	v_and_b32_e32 v147, 0xffff0000, v227
	v_pk_add_f32 v[14:15], v[14:15], v[144:145]
	v_pk_add_f32 v[16:17], v[16:17], v[146:147]
	v_lshlrev_b32_e32 v144, 16, v228
	v_and_b32_e32 v145, 0xffff0000, v228
	v_lshlrev_b32_e32 v146, 16, v229
	v_and_b32_e32 v147, 0xffff0000, v229
	v_pk_add_f32 v[10:11], v[10:11], v[144:145]
	v_pk_add_f32 v[12:13], v[12:13], v[146:147]
	v_cvt_pk_bf16_f32 v176, v14, v15
	v_cvt_pk_bf16_f32 v177, v16, v17
	v_cvt_pk_bf16_f32 v178, v10, v11
	v_cvt_pk_bf16_f32 v179, v12, v13
	v_mad_u64_u32 v[144:145], vcc, s30, 11, v[132:133]
	global_store_dwordx4 v[144:145], v[176:179], off
	s_waitcnt vmcnt(7)
	v_lshlrev_b32_e32 v144, 16, v198
	v_and_b32_e32 v145, 0xffff0000, v198
	v_lshlrev_b32_e32 v146, 16, v199
	v_and_b32_e32 v147, 0xffff0000, v199
	v_mul_f32_e32 v144, 0xbfb8aa3b, v144
	v_mul_f32_e32 v145, 0xbfb8aa3b, v145
	v_mul_f32_e32 v146, 0xbfb8aa3b, v146
	v_mul_f32_e32 v147, 0xbfb8aa3b, v147
	v_exp_f32_e32 v144, v144
	v_exp_f32_e32 v145, v145
	v_exp_f32_e32 v146, v146
	v_exp_f32_e32 v147, v147
	v_pk_add_f32 v[144:145], v[144:145], 1.0 op_sel_hi:[1,0]
	v_pk_add_f32 v[146:147], v[146:147], 1.0 op_sel_hi:[1,0]
	v_rcp_f32_e32 v144, v144
	v_rcp_f32_e32 v145, v145
	v_rcp_f32_e32 v146, v146
	v_rcp_f32_e32 v147, v147
	v_pk_mul_f32 v[6:7], v[6:7], v[144:145]
	v_pk_mul_f32 v[8:9], v[8:9], v[146:147]
	v_lshlrev_b32_e32 v144, 16, v200
	v_and_b32_e32 v145, 0xffff0000, v200
	v_lshlrev_b32_e32 v146, 16, v201
	v_and_b32_e32 v147, 0xffff0000, v201
	v_mul_f32_e32 v144, 0xbfb8aa3b, v144
	v_mul_f32_e32 v145, 0xbfb8aa3b, v145
	v_mul_f32_e32 v146, 0xbfb8aa3b, v146
	v_mul_f32_e32 v147, 0xbfb8aa3b, v147
	v_exp_f32_e32 v144, v144
	v_exp_f32_e32 v145, v145
	v_exp_f32_e32 v146, v146
	v_exp_f32_e32 v147, v147
	v_pk_add_f32 v[144:145], v[144:145], 1.0 op_sel_hi:[1,0]
	v_pk_add_f32 v[146:147], v[146:147], 1.0 op_sel_hi:[1,0]
	v_rcp_f32_e32 v144, v144
	v_rcp_f32_e32 v145, v145
	v_rcp_f32_e32 v146, v146
	v_rcp_f32_e32 v147, v147
	v_pk_mul_f32 v[2:3], v[2:3], v[144:145]
	v_pk_mul_f32 v[4:5], v[4:5], v[146:147]
	v_lshlrev_b32_e32 v144, 16, v248
	v_and_b32_e32 v145, 0xffff0000, v248
	v_lshlrev_b32_e32 v146, 16, v249
	v_and_b32_e32 v147, 0xffff0000, v249
	v_pk_add_f32 v[6:7], v[6:7], v[144:145]
	v_pk_add_f32 v[8:9], v[8:9], v[146:147]
	v_lshlrev_b32_e32 v144, 16, v250
	v_and_b32_e32 v145, 0xffff0000, v250
	v_lshlrev_b32_e32 v146, 16, v251
	v_and_b32_e32 v147, 0xffff0000, v251
	v_pk_add_f32 v[2:3], v[2:3], v[144:145]
	v_pk_add_f32 v[4:5], v[4:5], v[146:147]
	v_cvt_pk_bf16_f32 v198, v6, v7
	v_cvt_pk_bf16_f32 v199, v8, v9
	v_cvt_pk_bf16_f32 v200, v2, v3
	v_cvt_pk_bf16_f32 v201, v4, v5
	v_mad_u64_u32 v[144:145], vcc, s30, 11, v[132:133]
	global_store_dwordx4 v[144:145], v[198:201], off offset:256
	s_branch .Lg5_epi_done
; __device__ __forceinline__ unsigned cvt_pk_bf16(float lo, float hi) { f32x2e v = {lo, hi}; bf16x2e b = __builtin_convertvector(v, bf16x2e); return __builtin_bit_cast(unsigned, b); }
; __device__ __forceinline__ float bflo(unsigned w) { return __uint_as_float(w << 16); }
; __device__ __forceinline__ float bfhi(unsigned w) { return __uint_as_float(w & 0xffff0000u); }
; __device__ __forceinline__ float sigm(float x) { return 1.0f / (1.0f + __expf(-x)); }
; __device__ __forceinline__ float bflo(unsigned w) { return __uint_as_float(w << 16); }
; __device__ __forceinline__ float bfhi(unsigned w) { return __uint_as_float(w & 0xffff0000u); }
; __device__ __forceinline__ float sigm(float x) { return 1.0f / (1.0f + __expf(-x)); }
;     __device__ __forceinline__ void operator()(const f32x4 (&acc)[2][2][4][2], const Unit& u, int wr, int wc, int fr, int fq) const {
;     ...
;             for (int m = 0; m < 4; ++m) { const size_t row = (size_t)(row0 + ai * HALF + m * 16);
; #pragma unroll
;                 for (int bj = 0; bj < 2; ++bj) { const f32x4 v0 = acc[ai][bj][m][0], v1 = acc[ai][bj][m][1];
;                     const u32x4 gw = *(const u32x4*)(G + row * ldg + col0 + bj * HALF);
;                     float r[8];
;                     r[0] = sigm(bflo(gw.x)) * v0[0]; r[1] = sigm(bfhi(gw.x)) * v0[1]; r[2] = sigm(bflo(gw.y)) * v0[2]; r[3] = sigm(bfhi(gw.y)) * v0[3];
;                     r[4] = sigm(bflo(gw.z)) * v1[0]; r[5] = sigm(bfhi(gw.z)) * v1[1]; r[6] = sigm(bflo(gw.w)) * v1[2]; r[7] = sigm(bfhi(gw.w)) * v1[3];
;                     bf16_t* op = O + row * ldo + col0 + bj * HALF;
;                     if (!first) { const u32x4 ow = *(const u32x4*)op;
;                         r[0] += bflo(ow.x); r[1] += bfhi(ow.x); r[2] += bflo(ow.y); r[3] += bfhi(ow.y); r[4] += bflo(ow.z); r[5] += bfhi(ow.z); r[6] += bflo(ow.w); r[7] += bfhi(ow.w); }
;                     u32x4 w; w.x = cvt_pk_bf16(r[0], r[1]); w.y = cvt_pk_bf16(r[2], r[3]); w.z = cvt_pk_bf16(r[4], r[5]); w.w = cvt_pk_bf16(r[6], r[7]);
;                     *(u32x4*)op = w; } }
.Lg5_epi_first:
	global_load_dwordx4 v[148:151], v[130:131], off
	global_load_dwordx4 v[156:159], v[130:131], off offset:256
	v_mad_u64_u32 v[146:147], vcc, s31, 1, v[130:131]
	global_load_dwordx4 v[160:163], v[146:147], off
	v_mad_u64_u32 v[146:147], vcc, s31, 1, v[130:131]
	global_load_dwordx4 v[164:167], v[146:147], off offset:256
	v_mad_u64_u32 v[146:147], vcc, s31, 2, v[130:131]
	global_load_dwordx4 v[168:171], v[146:147], off
	v_mad_u64_u32 v[146:147], vcc, s31, 2, v[130:131]
	global_load_dwordx4 v[172:175], v[146:147], off offset:256
	v_mad_u64_u32 v[146:147], vcc, s31, 3, v[130:131]
	global_load_dwordx4 v[176:179], v[146:147], off
	v_mad_u64_u32 v[146:147], vcc, s31, 3, v[130:131]
	global_load_dwordx4 v[198:201], v[146:147], off offset:256
	v_mad_u64_u32 v[146:147], vcc, s31, 8, v[130:131]
	global_load_dwordx4 v[202:205], v[146:147], off
	v_mad_u64_u32 v[146:147], vcc, s31, 8, v[130:131]
	global_load_dwordx4 v[206:209], v[146:147], off offset:256
	v_mad_u64_u32 v[146:147], vcc, s31, 9, v[130:131]
	global_load_dwordx4 v[210:213], v[146:147], off
	v_mad_u64_u32 v[146:147], vcc, s31, 9, v[130:131]
	global_load_dwordx4 v[214:217], v[146:147], off offset:256
	v_mad_u64_u32 v[146:147], vcc, s31, 10, v[130:131]
	global_load_dwordx4 v[218:221], v[146:147], off
	v_mad_u64_u32 v[146:147], vcc, s31, 10, v[130:131]
	global_load_dwordx4 v[222:225], v[146:147], off offset:256
	v_mad_u64_u32 v[146:147], vcc, s31, 11, v[130:131]
	global_load_dwordx4 v[226:229], v[146:147], off
	v_mad_u64_u32 v[146:147], vcc, s31, 11, v[130:131]
	global_load_dwordx4 v[248:251], v[146:147], off offset:256
	s_waitcnt vmcnt(15)
	v_lshlrev_b32_e32 v144, 16, v148
	v_and_b32_e32 v145, 0xffff0000, v148
	v_lshlrev_b32_e32 v146, 16, v149
	v_and_b32_e32 v147, 0xffff0000, v149
	v_mul_f32_e32 v144, 0xbfb8aa3b, v144
	v_mul_f32_e32 v145, 0xbfb8aa3b, v145
	v_mul_f32_e32 v146, 0xbfb8aa3b, v146
	v_mul_f32_e32 v147, 0xbfb8aa3b, v147
	v_exp_f32_e32 v144, v144
	v_exp_f32_e32 v145, v145
	v_exp_f32_e32 v146, v146
	v_exp_f32_e32 v147, v147
	v_pk_add_f32 v[144:145], v[144:145], 1.0 op_sel_hi:[1,0]
	v_pk_add_f32 v[146:147], v[146:147], 1.0 op_sel_hi:[1,0]
	v_rcp_f32_e32 v144, v144
	v_rcp_f32_e32 v145, v145
	v_rcp_f32_e32 v146, v146
	v_rcp_f32_e32 v147, v147
	v_pk_mul_f32 v[126:127], v[126:127], v[144:145]
	v_pk_mul_f32 v[128:129], v[128:129], v[146:147]
	v_lshlrev_b32_e32 v144, 16, v150
	v_and_b32_e32 v145, 0xffff0000, v150
	v_lshlrev_b32_e32 v146, 16, v151
	v_and_b32_e32 v147, 0xffff0000, v151
	v_mul_f32_e32 v144, 0xbfb8aa3b, v144
	v_mul_f32_e32 v145, 0xbfb8aa3b, v145
	v_mul_f32_e32 v146, 0xbfb8aa3b, v146
	v_mul_f32_e32 v147, 0xbfb8aa3b, v147
	v_exp_f32_e32 v144, v144
	v_exp_f32_e32 v145, v145
	v_exp_f32_e32 v146, v146
	v_exp_f32_e32 v147, v147
	v_pk_add_f32 v[144:145], v[144:145], 1.0 op_sel_hi:[1,0]
	v_pk_add_f32 v[146:147], v[146:147], 1.0 op_sel_hi:[1,0]
	v_rcp_f32_e32 v144, v144
	v_rcp_f32_e32 v145, v145
	v_rcp_f32_e32 v146, v146
	v_rcp_f32_e32 v147, v147
	v_pk_mul_f32 v[122:123], v[122:123], v[144:145]
	v_pk_mul_f32 v[124:125], v[124:125], v[146:147]
	v_cvt_pk_bf16_f32 v148, v126, v127
	v_cvt_pk_bf16_f32 v149, v128, v129
	v_cvt_pk_bf16_f32 v150, v122, v123
	v_cvt_pk_bf16_f32 v151, v124, v125
	s_nop 0
	global_store_dwordx4 v[132:133], v[148:151], off
	s_waitcnt vmcnt(15)
	v_lshlrev_b32_e32 v144, 16, v156
	v_and_b32_e32 v145, 0xffff0000, v156
	v_lshlrev_b32_e32 v146, 16, v157
	v_and_b32_e32 v147, 0xffff0000, v157
	v_mul_f32_e32 v144, 0xbfb8aa3b, v144
	v_mul_f32_e32 v145, 0xbfb8aa3b, v145
	v_mul_f32_e32 v146, 0xbfb8aa3b, v146
	v_mul_f32_e32 v147, 0xbfb8aa3b, v147
	v_exp_f32_e32 v144, v144
	v_exp_f32_e32 v145, v145
	v_exp_f32_e32 v146, v146
	v_exp_f32_e32 v147, v147
	v_pk_add_f32 v[144:145], v[144:145], 1.0 op_sel_hi:[1,0]
	v_pk_add_f32 v[146:147], v[146:147], 1.0 op_sel_hi:[1,0]
	v_rcp_f32_e32 v144, v144
	v_rcp_f32_e32 v145, v145
	v_rcp_f32_e32 v146, v146
	v_rcp_f32_e32 v147, v147
	v_pk_mul_f32 v[118:119], v[118:119], v[144:145]
	v_pk_mul_f32 v[120:121], v[120:121], v[146:147]
	v_lshlrev_b32_e32 v144, 16, v158
	v_and_b32_e32 v145, 0xffff0000, v158
	v_lshlrev_b32_e32 v146, 16, v159
	v_and_b32_e32 v147, 0xffff0000, v159
	v_mul_f32_e32 v144, 0xbfb8aa3b, v144
	v_mul_f32_e32 v145, 0xbfb8aa3b, v145
	v_mul_f32_e32 v146, 0xbfb8aa3b, v146
	v_mul_f32_e32 v147, 0xbfb8aa3b, v147
	v_exp_f32_e32 v144, v144
	v_exp_f32_e32 v145, v145
	v_exp_f32_e32 v146, v146
	v_exp_f32_e32 v147, v147
	v_pk_add_f32 v[144:145], v[144:145], 1.0 op_sel_hi:[1,0]
	v_pk_add_f32 v[146:147], v[146:147], 1.0 op_sel_hi:[1,0]
	v_rcp_f32_e32 v144, v144
	v_rcp_f32_e32 v145, v145
	v_rcp_f32_e32 v146, v146
	v_rcp_f32_e32 v147, v147
	v_pk_mul_f32 v[114:115], v[114:115], v[144:145]
	v_pk_mul_f32 v[116:117], v[116:117], v[146:147]
	v_cvt_pk_bf16_f32 v156, v118, v119
	v_cvt_pk_bf16_f32 v157, v120, v121
	v_cvt_pk_bf16_f32 v158, v114, v115
	v_cvt_pk_bf16_f32 v159, v116, v117
	s_nop 0
	global_store_dwordx4 v[132:133], v[156:159], off offset:256
	s_waitcnt vmcnt(15)
; __device__ __forceinline__ unsigned cvt_pk_bf16(float lo, float hi) { f32x2e v = {lo, hi}; bf16x2e b = __builtin_convertvector(v, bf16x2e); return __builtin_bit_cast(unsigned, b); }
; __device__ __forceinline__ float bflo(unsigned w) { return __uint_as_float(w << 16); }
; __device__ __forceinline__ float bfhi(unsigned w) { return __uint_as_float(w & 0xffff0000u); }
; __device__ __forceinline__ float sigm(float x) { return 1.0f / (1.0f + __expf(-x)); }
; __device__ __forceinline__ float bflo(unsigned w) { return __uint_as_float(w << 16); }
; __device__ __forceinline__ float bfhi(unsigned w) { return __uint_as_float(w & 0xffff0000u); }
; __device__ __forceinline__ float sigm(float x) { return 1.0f / (1.0f + __expf(-x)); }
;     __device__ __forceinline__ void operator()(const f32x4 (&acc)[2][2][4][2], const Unit& u, int wr, int wc, int fr, int fq) const {
;     ...
;             for (int m = 0; m < 4; ++m) { const size_t row = (size_t)(row0 + ai * HALF + m * 16);
; #pragma unroll
;                 for (int bj = 0; bj < 2; ++bj) { const f32x4 v0 = acc[ai][bj][m][0], v1 = acc[ai][bj][m][1];
;                     const u32x4 gw = *(const u32x4*)(G + row * ldg + col0 + bj * HALF);
;                     float r[8];
;                     r[0] = sigm(bflo(gw.x)) * v0[0]; r[1] = sigm(bfhi(gw.x)) * v0[1]; r[2] = sigm(bflo(gw.y)) * v0[2]; r[3] = sigm(bfhi(gw.y)) * v0[3];
;                     r[4] = sigm(bflo(gw.z)) * v1[0]; r[5] = sigm(bfhi(gw.z)) * v1[1]; r[6] = sigm(bflo(gw.w)) * v1[2]; r[7] = sigm(bfhi(gw.w)) * v1[3];
;                     bf16_t* op = O + row * ldo + col0 + bj * HALF;
;                     if (!first) { const u32x4 ow = *(const u32x4*)op;
;                         r[0] += bflo(ow.x); r[1] += bfhi(ow.x); r[2] += bflo(ow.y); r[3] += bfhi(ow.y); r[4] += bflo(ow.z); r[5] += bfhi(ow.z); r[6] += bflo(ow.w); r[7] += bfhi(ow.w); }
;                     u32x4 w; w.x = cvt_pk_bf16(r[0], r[1]); w.y = cvt_pk_bf16(r[2], r[3]); w.z = cvt_pk_bf16(r[4], r[5]); w.w = cvt_pk_bf16(r[6], r[7]);
;                     *(u32x4*)op = w; } }
	v_lshlrev_b32_e32 v144, 16, v160
	v_and_b32_e32 v145, 0xffff0000, v160
	v_lshlrev_b32_e32 v146, 16, v161
	v_and_b32_e32 v147, 0xffff0000, v161
	v_mul_f32_e32 v144, 0xbfb8aa3b, v144
	v_mul_f32_e32 v145, 0xbfb8aa3b, v145
	v_mul_f32_e32 v146, 0xbfb8aa3b, v146
	v_mul_f32_e32 v147, 0xbfb8aa3b, v147
	v_exp_f32_e32 v144, v144
	v_exp_f32_e32 v145, v145
	v_exp_f32_e32 v146, v146
	v_exp_f32_e32 v147, v147
	v_pk_add_f32 v[144:145], v[144:145], 1.0 op_sel_hi:[1,0]
	v_pk_add_f32 v[146:147], v[146:147], 1.0 op_sel_hi:[1,0]
	v_rcp_f32_e32 v144, v144
	v_rcp_f32_e32 v145, v145
	v_rcp_f32_e32 v146, v146
	v_rcp_f32_e32 v147, v147
	v_pk_mul_f32 v[110:111], v[110:111], v[144:145]
	v_pk_mul_f32 v[112:113], v[112:113], v[146:147]
	v_lshlrev_b32_e32 v144, 16, v162
	v_and_b32_e32 v145, 0xffff0000, v162
	v_lshlrev_b32_e32 v146, 16, v163
	v_and_b32_e32 v147, 0xffff0000, v163
	v_mul_f32_e32 v144, 0xbfb8aa3b, v144
	v_mul_f32_e32 v145, 0xbfb8aa3b, v145
	v_mul_f32_e32 v146, 0xbfb8aa3b, v146
	v_mul_f32_e32 v147, 0xbfb8aa3b, v147
	v_exp_f32_e32 v144, v144
	v_exp_f32_e32 v145, v145
	v_exp_f32_e32 v146, v146
	v_exp_f32_e32 v147, v147
	v_pk_add_f32 v[144:145], v[144:145], 1.0 op_sel_hi:[1,0]
	v_pk_add_f32 v[146:147], v[146:147], 1.0 op_sel_hi:[1,0]
	v_rcp_f32_e32 v144, v144
	v_rcp_f32_e32 v145, v145
	v_rcp_f32_e32 v146, v146
	v_rcp_f32_e32 v147, v147
	v_pk_mul_f32 v[106:107], v[106:107], v[144:145]
	v_pk_mul_f32 v[108:109], v[108:109], v[146:147]
	v_cvt_pk_bf16_f32 v160, v110, v111
	v_cvt_pk_bf16_f32 v161, v112, v113
	v_cvt_pk_bf16_f32 v162, v106, v107
	v_cvt_pk_bf16_f32 v163, v108, v109
	v_mad_u64_u32 v[144:145], vcc, s30, 1, v[132:133]
	global_store_dwordx4 v[144:145], v[160:163], off
	s_waitcnt vmcnt(15)
	v_lshlrev_b32_e32 v144, 16, v164
	v_and_b32_e32 v145, 0xffff0000, v164
	v_lshlrev_b32_e32 v146, 16, v165
	v_and_b32_e32 v147, 0xffff0000, v165
	v_mul_f32_e32 v144, 0xbfb8aa3b, v144
	v_mul_f32_e32 v145, 0xbfb8aa3b, v145
	v_mul_f32_e32 v146, 0xbfb8aa3b, v146
	v_mul_f32_e32 v147, 0xbfb8aa3b, v147
	v_exp_f32_e32 v144, v144
	v_exp_f32_e32 v145, v145
	v_exp_f32_e32 v146, v146
	v_exp_f32_e32 v147, v147
	v_pk_add_f32 v[144:145], v[144:145], 1.0 op_sel_hi:[1,0]
	v_pk_add_f32 v[146:147], v[146:147], 1.0 op_sel_hi:[1,0]
	v_rcp_f32_e32 v144, v144
	v_rcp_f32_e32 v145, v145
	v_rcp_f32_e32 v146, v146
	v_rcp_f32_e32 v147, v147
	v_pk_mul_f32 v[102:103], v[102:103], v[144:145]
	v_pk_mul_f32 v[104:105], v[104:105], v[146:147]
	v_lshlrev_b32_e32 v144, 16, v166
	v_and_b32_e32 v145, 0xffff0000, v166
	v_lshlrev_b32_e32 v146, 16, v167
	v_and_b32_e32 v147, 0xffff0000, v167
	v_mul_f32_e32 v144, 0xbfb8aa3b, v144
	v_mul_f32_e32 v145, 0xbfb8aa3b, v145
	v_mul_f32_e32 v146, 0xbfb8aa3b, v146
	v_mul_f32_e32 v147, 0xbfb8aa3b, v147
	v_exp_f32_e32 v144, v144
	v_exp_f32_e32 v145, v145
	v_exp_f32_e32 v146, v146
	v_exp_f32_e32 v147, v147
	v_pk_add_f32 v[144:145], v[144:145], 1.0 op_sel_hi:[1,0]
	v_pk_add_f32 v[146:147], v[146:147], 1.0 op_sel_hi:[1,0]
	v_rcp_f32_e32 v144, v144
	v_rcp_f32_e32 v145, v145
	v_rcp_f32_e32 v146, v146
	v_rcp_f32_e32 v147, v147
	v_pk_mul_f32 v[98:99], v[98:99], v[144:145]
	v_pk_mul_f32 v[100:101], v[100:101], v[146:147]
	v_cvt_pk_bf16_f32 v164, v102, v103
	v_cvt_pk_bf16_f32 v165, v104, v105
	v_cvt_pk_bf16_f32 v166, v98, v99
	v_cvt_pk_bf16_f32 v167, v100, v101
	v_mad_u64_u32 v[144:145], vcc, s30, 1, v[132:133]
	global_store_dwordx4 v[144:145], v[164:167], off offset:256
	s_waitcnt vmcnt(15)
	v_lshlrev_b32_e32 v144, 16, v168
	v_and_b32_e32 v145, 0xffff0000, v168
	v_lshlrev_b32_e32 v146, 16, v169
	v_and_b32_e32 v147, 0xffff0000, v169
	v_mul_f32_e32 v144, 0xbfb8aa3b, v144
	v_mul_f32_e32 v145, 0xbfb8aa3b, v145
	v_mul_f32_e32 v146, 0xbfb8aa3b, v146
	v_mul_f32_e32 v147, 0xbfb8aa3b, v147
	v_exp_f32_e32 v144, v144
	v_exp_f32_e32 v145, v145
	v_exp_f32_e32 v146, v146
	v_exp_f32_e32 v147, v147
	v_pk_add_f32 v[144:145], v[144:145], 1.0 op_sel_hi:[1,0]
	v_pk_add_f32 v[146:147], v[146:147], 1.0 op_sel_hi:[1,0]
	v_rcp_f32_e32 v144, v144
	v_rcp_f32_e32 v145, v145
	v_rcp_f32_e32 v146, v146
	v_rcp_f32_e32 v147, v147
	v_pk_mul_f32 v[94:95], v[94:95], v[144:145]
	v_pk_mul_f32 v[96:97], v[96:97], v[146:147]
	v_lshlrev_b32_e32 v144, 16, v170
	v_and_b32_e32 v145, 0xffff0000, v170
	v_lshlrev_b32_e32 v146, 16, v171
	v_and_b32_e32 v147, 0xffff0000, v171
	v_mul_f32_e32 v144, 0xbfb8aa3b, v144
	v_mul_f32_e32 v145, 0xbfb8aa3b, v145
	v_mul_f32_e32 v146, 0xbfb8aa3b, v146
	v_mul_f32_e32 v147, 0xbfb8aa3b, v147
	v_exp_f32_e32 v144, v144
	v_exp_f32_e32 v145, v145
	v_exp_f32_e32 v146, v146
	v_exp_f32_e32 v147, v147
	v_pk_add_f32 v[144:145], v[144:145], 1.0 op_sel_hi:[1,0]
	v_pk_add_f32 v[146:147], v[146:147], 1.0 op_sel_hi:[1,0]
	v_rcp_f32_e32 v144, v144
	v_rcp_f32_e32 v145, v145
	v_rcp_f32_e32 v146, v146
	v_rcp_f32_e32 v147, v147
	v_pk_mul_f32 v[90:91], v[90:91], v[144:145]
	v_pk_mul_f32 v[92:93], v[92:93], v[146:147]
	v_cvt_pk_bf16_f32 v168, v94, v95
	v_cvt_pk_bf16_f32 v169, v96, v97
	v_cvt_pk_bf16_f32 v170, v90, v91
	v_cvt_pk_bf16_f32 v171, v92, v93
	v_mad_u64_u32 v[144:145], vcc, s30, 2, v[132:133]
	global_store_dwordx4 v[144:145], v[168:171], off
	s_waitcnt vmcnt(15)
; __device__ __forceinline__ unsigned cvt_pk_bf16(float lo, float hi) { f32x2e v = {lo, hi}; bf16x2e b = __builtin_convertvector(v, bf16x2e); return __builtin_bit_cast(unsigned, b); }
; __device__ __forceinline__ float bflo(unsigned w) { return __uint_as_float(w << 16); }
; __device__ __forceinline__ float bfhi(unsigned w) { return __uint_as_float(w & 0xffff0000u); }
; __device__ __forceinline__ float sigm(float x) { return 1.0f / (1.0f + __expf(-x)); }
; __device__ __forceinline__ float bflo(unsigned w) { return __uint_as_float(w << 16); }
; __device__ __forceinline__ float bfhi(unsigned w) { return __uint_as_float(w & 0xffff0000u); }
; __device__ __forceinline__ float sigm(float x) { return 1.0f / (1.0f + __expf(-x)); }
;     __device__ __forceinline__ void operator()(const f32x4 (&acc)[2][2][4][2], const Unit& u, int wr, int wc, int fr, int fq) const {
;     ...
;             for (int m = 0; m < 4; ++m) { const size_t row = (size_t)(row0 + ai * HALF + m * 16);
; #pragma unroll
;                 for (int bj = 0; bj < 2; ++bj) { const f32x4 v0 = acc[ai][bj][m][0], v1 = acc[ai][bj][m][1];
;                     const u32x4 gw = *(const u32x4*)(G + row * ldg + col0 + bj * HALF);
;                     float r[8];
;                     r[0] = sigm(bflo(gw.x)) * v0[0]; r[1] = sigm(bfhi(gw.x)) * v0[1]; r[2] = sigm(bflo(gw.y)) * v0[2]; r[3] = sigm(bfhi(gw.y)) * v0[3];
;                     r[4] = sigm(bflo(gw.z)) * v1[0]; r[5] = sigm(bfhi(gw.z)) * v1[1]; r[6] = sigm(bflo(gw.w)) * v1[2]; r[7] = sigm(bfhi(gw.w)) * v1[3];
;                     bf16_t* op = O + row * ldo + col0 + bj * HALF;
;                     if (!first) { const u32x4 ow = *(const u32x4*)op;
;                         r[0] += bflo(ow.x); r[1] += bfhi(ow.x); r[2] += bflo(ow.y); r[3] += bfhi(ow.y); r[4] += bflo(ow.z); r[5] += bfhi(ow.z); r[6] += bflo(ow.w); r[7] += bfhi(ow.w); }
;                     u32x4 w; w.x = cvt_pk_bf16(r[0], r[1]); w.y = cvt_pk_bf16(r[2], r[3]); w.z = cvt_pk_bf16(r[4], r[5]); w.w = cvt_pk_bf16(r[6], r[7]);
;                     *(u32x4*)op = w; } }
	v_lshlrev_b32_e32 v144, 16, v172
	v_and_b32_e32 v145, 0xffff0000, v172
	v_lshlrev_b32_e32 v146, 16, v173
	v_and_b32_e32 v147, 0xffff0000, v173
	v_mul_f32_e32 v144, 0xbfb8aa3b, v144
	v_mul_f32_e32 v145, 0xbfb8aa3b, v145
	v_mul_f32_e32 v146, 0xbfb8aa3b, v146
	v_mul_f32_e32 v147, 0xbfb8aa3b, v147
	v_exp_f32_e32 v144, v144
	v_exp_f32_e32 v145, v145
	v_exp_f32_e32 v146, v146
	v_exp_f32_e32 v147, v147
	v_pk_add_f32 v[144:145], v[144:145], 1.0 op_sel_hi:[1,0]
	v_pk_add_f32 v[146:147], v[146:147], 1.0 op_sel_hi:[1,0]
	v_rcp_f32_e32 v144, v144
	v_rcp_f32_e32 v145, v145
	v_rcp_f32_e32 v146, v146
	v_rcp_f32_e32 v147, v147
	v_pk_mul_f32 v[86:87], v[86:87], v[144:145]
	v_pk_mul_f32 v[88:89], v[88:89], v[146:147]
	v_lshlrev_b32_e32 v144, 16, v174
	v_and_b32_e32 v145, 0xffff0000, v174
	v_lshlrev_b32_e32 v146, 16, v175
	v_and_b32_e32 v147, 0xffff0000, v175
	v_mul_f32_e32 v144, 0xbfb8aa3b, v144
	v_mul_f32_e32 v145, 0xbfb8aa3b, v145
	v_mul_f32_e32 v146, 0xbfb8aa3b, v146
	v_mul_f32_e32 v147, 0xbfb8aa3b, v147
	v_exp_f32_e32 v144, v144
	v_exp_f32_e32 v145, v145
	v_exp_f32_e32 v146, v146
	v_exp_f32_e32 v147, v147
	v_pk_add_f32 v[144:145], v[144:145], 1.0 op_sel_hi:[1,0]
	v_pk_add_f32 v[146:147], v[146:147], 1.0 op_sel_hi:[1,0]
	v_rcp_f32_e32 v144, v144
	v_rcp_f32_e32 v145, v145
	v_rcp_f32_e32 v146, v146
	v_rcp_f32_e32 v147, v147
	v_pk_mul_f32 v[82:83], v[82:83], v[144:145]
	v_pk_mul_f32 v[84:85], v[84:85], v[146:147]
	v_cvt_pk_bf16_f32 v172, v86, v87
	v_cvt_pk_bf16_f32 v173, v88, v89
	v_cvt_pk_bf16_f32 v174, v82, v83
	v_cvt_pk_bf16_f32 v175, v84, v85
	v_mad_u64_u32 v[144:145], vcc, s30, 2, v[132:133]
	global_store_dwordx4 v[144:145], v[172:175], off offset:256
	s_waitcnt vmcnt(15)
	v_lshlrev_b32_e32 v144, 16, v176
	v_and_b32_e32 v145, 0xffff0000, v176
	v_lshlrev_b32_e32 v146, 16, v177
	v_and_b32_e32 v147, 0xffff0000, v177
	v_mul_f32_e32 v144, 0xbfb8aa3b, v144
	v_mul_f32_e32 v145, 0xbfb8aa3b, v145
	v_mul_f32_e32 v146, 0xbfb8aa3b, v146
	v_mul_f32_e32 v147, 0xbfb8aa3b, v147
	v_exp_f32_e32 v144, v144
	v_exp_f32_e32 v145, v145
	v_exp_f32_e32 v146, v146
	v_exp_f32_e32 v147, v147
	v_pk_add_f32 v[144:145], v[144:145], 1.0 op_sel_hi:[1,0]
	v_pk_add_f32 v[146:147], v[146:147], 1.0 op_sel_hi:[1,0]
	v_rcp_f32_e32 v144, v144
	v_rcp_f32_e32 v145, v145
	v_rcp_f32_e32 v146, v146
	v_rcp_f32_e32 v147, v147
	v_pk_mul_f32 v[78:79], v[78:79], v[144:145]
	v_pk_mul_f32 v[80:81], v[80:81], v[146:147]
	v_lshlrev_b32_e32 v144, 16, v178
	v_and_b32_e32 v145, 0xffff0000, v178
	v_lshlrev_b32_e32 v146, 16, v179
	v_and_b32_e32 v147, 0xffff0000, v179
	v_mul_f32_e32 v144, 0xbfb8aa3b, v144
	v_mul_f32_e32 v145, 0xbfb8aa3b, v145
	v_mul_f32_e32 v146, 0xbfb8aa3b, v146
	v_mul_f32_e32 v147, 0xbfb8aa3b, v147
	v_exp_f32_e32 v144, v144
	v_exp_f32_e32 v145, v145
	v_exp_f32_e32 v146, v146
	v_exp_f32_e32 v147, v147
	v_pk_add_f32 v[144:145], v[144:145], 1.0 op_sel_hi:[1,0]
	v_pk_add_f32 v[146:147], v[146:147], 1.0 op_sel_hi:[1,0]
	v_rcp_f32_e32 v144, v144
	v_rcp_f32_e32 v145, v145
	v_rcp_f32_e32 v146, v146
	v_rcp_f32_e32 v147, v147
	v_pk_mul_f32 v[74:75], v[74:75], v[144:145]
	v_pk_mul_f32 v[76:77], v[76:77], v[146:147]
	v_cvt_pk_bf16_f32 v176, v78, v79
	v_cvt_pk_bf16_f32 v177, v80, v81
	v_cvt_pk_bf16_f32 v178, v74, v75
	v_cvt_pk_bf16_f32 v179, v76, v77
	v_mad_u64_u32 v[144:145], vcc, s30, 3, v[132:133]
	global_store_dwordx4 v[144:145], v[176:179], off
	s_waitcnt vmcnt(15)
	v_lshlrev_b32_e32 v144, 16, v198
	v_and_b32_e32 v145, 0xffff0000, v198
	v_lshlrev_b32_e32 v146, 16, v199
	v_and_b32_e32 v147, 0xffff0000, v199
	v_mul_f32_e32 v144, 0xbfb8aa3b, v144
	v_mul_f32_e32 v145, 0xbfb8aa3b, v145
	v_mul_f32_e32 v146, 0xbfb8aa3b, v146
	v_mul_f32_e32 v147, 0xbfb8aa3b, v147
	v_exp_f32_e32 v144, v144
	v_exp_f32_e32 v145, v145
	v_exp_f32_e32 v146, v146
	v_exp_f32_e32 v147, v147
	v_pk_add_f32 v[144:145], v[144:145], 1.0 op_sel_hi:[1,0]
	v_pk_add_f32 v[146:147], v[146:147], 1.0 op_sel_hi:[1,0]
	v_rcp_f32_e32 v144, v144
	v_rcp_f32_e32 v145, v145
	v_rcp_f32_e32 v146, v146
	v_rcp_f32_e32 v147, v147
	v_pk_mul_f32 v[70:71], v[70:71], v[144:145]
	v_pk_mul_f32 v[72:73], v[72:73], v[146:147]
	v_lshlrev_b32_e32 v144, 16, v200
	v_and_b32_e32 v145, 0xffff0000, v200
	v_lshlrev_b32_e32 v146, 16, v201
	v_and_b32_e32 v147, 0xffff0000, v201
	v_mul_f32_e32 v144, 0xbfb8aa3b, v144
	v_mul_f32_e32 v145, 0xbfb8aa3b, v145
	v_mul_f32_e32 v146, 0xbfb8aa3b, v146
	v_mul_f32_e32 v147, 0xbfb8aa3b, v147
	v_exp_f32_e32 v144, v144
	v_exp_f32_e32 v145, v145
	v_exp_f32_e32 v146, v146
	v_exp_f32_e32 v147, v147
	v_pk_add_f32 v[144:145], v[144:145], 1.0 op_sel_hi:[1,0]
	v_pk_add_f32 v[146:147], v[146:147], 1.0 op_sel_hi:[1,0]
	v_rcp_f32_e32 v144, v144
	v_rcp_f32_e32 v145, v145
	v_rcp_f32_e32 v146, v146
	v_rcp_f32_e32 v147, v147
	v_pk_mul_f32 v[66:67], v[66:67], v[144:145]
	v_pk_mul_f32 v[68:69], v[68:69], v[146:147]
	v_cvt_pk_bf16_f32 v198, v70, v71
	v_cvt_pk_bf16_f32 v199, v72, v73
	v_cvt_pk_bf16_f32 v200, v66, v67
	v_cvt_pk_bf16_f32 v201, v68, v69
	v_mad_u64_u32 v[144:145], vcc, s30, 3, v[132:133]
	global_store_dwordx4 v[144:145], v[198:201], off offset:256
	s_waitcnt vmcnt(15)
; __device__ __forceinline__ unsigned cvt_pk_bf16(float lo, float hi) { f32x2e v = {lo, hi}; bf16x2e b = __builtin_convertvector(v, bf16x2e); return __builtin_bit_cast(unsigned, b); }
; __device__ __forceinline__ float bflo(unsigned w) { return __uint_as_float(w << 16); }
; __device__ __forceinline__ float bfhi(unsigned w) { return __uint_as_float(w & 0xffff0000u); }
; __device__ __forceinline__ float sigm(float x) { return 1.0f / (1.0f + __expf(-x)); }
; __device__ __forceinline__ float bflo(unsigned w) { return __uint_as_float(w << 16); }
; __device__ __forceinline__ float bfhi(unsigned w) { return __uint_as_float(w & 0xffff0000u); }
; __device__ __forceinline__ float sigm(float x) { return 1.0f / (1.0f + __expf(-x)); }
;     __device__ __forceinline__ void operator()(const f32x4 (&acc)[2][2][4][2], const Unit& u, int wr, int wc, int fr, int fq) const {
;     ...
;             for (int m = 0; m < 4; ++m) { const size_t row = (size_t)(row0 + ai * HALF + m * 16);
; #pragma unroll
;                 for (int bj = 0; bj < 2; ++bj) { const f32x4 v0 = acc[ai][bj][m][0], v1 = acc[ai][bj][m][1];
;                     const u32x4 gw = *(const u32x4*)(G + row * ldg + col0 + bj * HALF);
;                     float r[8];
;                     r[0] = sigm(bflo(gw.x)) * v0[0]; r[1] = sigm(bfhi(gw.x)) * v0[1]; r[2] = sigm(bflo(gw.y)) * v0[2]; r[3] = sigm(bfhi(gw.y)) * v0[3];
;                     r[4] = sigm(bflo(gw.z)) * v1[0]; r[5] = sigm(bfhi(gw.z)) * v1[1]; r[6] = sigm(bflo(gw.w)) * v1[2]; r[7] = sigm(bfhi(gw.w)) * v1[3];
;                     bf16_t* op = O + row * ldo + col0 + bj * HALF;
;                     if (!first) { const u32x4 ow = *(const u32x4*)op;
;                         r[0] += bflo(ow.x); r[1] += bfhi(ow.x); r[2] += bflo(ow.y); r[3] += bfhi(ow.y); r[4] += bflo(ow.z); r[5] += bfhi(ow.z); r[6] += bflo(ow.w); r[7] += bfhi(ow.w); }
;                     u32x4 w; w.x = cvt_pk_bf16(r[0], r[1]); w.y = cvt_pk_bf16(r[2], r[3]); w.z = cvt_pk_bf16(r[4], r[5]); w.w = cvt_pk_bf16(r[6], r[7]);
;                     *(u32x4*)op = w; } }
	v_lshlrev_b32_e32 v144, 16, v202
	v_and_b32_e32 v145, 0xffff0000, v202
	v_lshlrev_b32_e32 v146, 16, v203
	v_and_b32_e32 v147, 0xffff0000, v203
	v_mul_f32_e32 v144, 0xbfb8aa3b, v144
	v_mul_f32_e32 v145, 0xbfb8aa3b, v145
	v_mul_f32_e32 v146, 0xbfb8aa3b, v146
	v_mul_f32_e32 v147, 0xbfb8aa3b, v147
	v_exp_f32_e32 v144, v144
	v_exp_f32_e32 v145, v145
	v_exp_f32_e32 v146, v146
	v_exp_f32_e32 v147, v147
	v_pk_add_f32 v[144:145], v[144:145], 1.0 op_sel_hi:[1,0]
	v_pk_add_f32 v[146:147], v[146:147], 1.0 op_sel_hi:[1,0]
	v_rcp_f32_e32 v144, v144
	v_rcp_f32_e32 v145, v145
	v_rcp_f32_e32 v146, v146
	v_rcp_f32_e32 v147, v147
	v_pk_mul_f32 v[62:63], v[62:63], v[144:145]
	v_pk_mul_f32 v[64:65], v[64:65], v[146:147]
	v_lshlrev_b32_e32 v144, 16, v204
	v_and_b32_e32 v145, 0xffff0000, v204
	v_lshlrev_b32_e32 v146, 16, v205
	v_and_b32_e32 v147, 0xffff0000, v205
	v_mul_f32_e32 v144, 0xbfb8aa3b, v144
	v_mul_f32_e32 v145, 0xbfb8aa3b, v145
	v_mul_f32_e32 v146, 0xbfb8aa3b, v146
	v_mul_f32_e32 v147, 0xbfb8aa3b, v147
	v_exp_f32_e32 v144, v144
	v_exp_f32_e32 v145, v145
	v_exp_f32_e32 v146, v146
	v_exp_f32_e32 v147, v147
	v_pk_add_f32 v[144:145], v[144:145], 1.0 op_sel_hi:[1,0]
	v_pk_add_f32 v[146:147], v[146:147], 1.0 op_sel_hi:[1,0]
	v_rcp_f32_e32 v144, v144
	v_rcp_f32_e32 v145, v145
	v_rcp_f32_e32 v146, v146
	v_rcp_f32_e32 v147, v147
	v_pk_mul_f32 v[58:59], v[58:59], v[144:145]
	v_pk_mul_f32 v[60:61], v[60:61], v[146:147]
	v_cvt_pk_bf16_f32 v202, v62, v63
	v_cvt_pk_bf16_f32 v203, v64, v65
	v_cvt_pk_bf16_f32 v204, v58, v59
	v_cvt_pk_bf16_f32 v205, v60, v61
	v_mad_u64_u32 v[144:145], vcc, s30, 8, v[132:133]
	global_store_dwordx4 v[144:145], v[202:205], off
	s_waitcnt vmcnt(15)
	v_lshlrev_b32_e32 v144, 16, v206
	v_and_b32_e32 v145, 0xffff0000, v206
	v_lshlrev_b32_e32 v146, 16, v207
	v_and_b32_e32 v147, 0xffff0000, v207
	v_mul_f32_e32 v144, 0xbfb8aa3b, v144
	v_mul_f32_e32 v145, 0xbfb8aa3b, v145
	v_mul_f32_e32 v146, 0xbfb8aa3b, v146
	v_mul_f32_e32 v147, 0xbfb8aa3b, v147
	v_exp_f32_e32 v144, v144
	v_exp_f32_e32 v145, v145
	v_exp_f32_e32 v146, v146
	v_exp_f32_e32 v147, v147
	v_pk_add_f32 v[144:145], v[144:145], 1.0 op_sel_hi:[1,0]
	v_pk_add_f32 v[146:147], v[146:147], 1.0 op_sel_hi:[1,0]
	v_rcp_f32_e32 v144, v144
	v_rcp_f32_e32 v145, v145
	v_rcp_f32_e32 v146, v146
	v_rcp_f32_e32 v147, v147
	v_pk_mul_f32 v[54:55], v[54:55], v[144:145]
	v_pk_mul_f32 v[56:57], v[56:57], v[146:147]
	v_lshlrev_b32_e32 v144, 16, v208
	v_and_b32_e32 v145, 0xffff0000, v208
	v_lshlrev_b32_e32 v146, 16, v209
	v_and_b32_e32 v147, 0xffff0000, v209
	v_mul_f32_e32 v144, 0xbfb8aa3b, v144
	v_mul_f32_e32 v145, 0xbfb8aa3b, v145
	v_mul_f32_e32 v146, 0xbfb8aa3b, v146
	v_mul_f32_e32 v147, 0xbfb8aa3b, v147
	v_exp_f32_e32 v144, v144
	v_exp_f32_e32 v145, v145
	v_exp_f32_e32 v146, v146
	v_exp_f32_e32 v147, v147
	v_pk_add_f32 v[144:145], v[144:145], 1.0 op_sel_hi:[1,0]
	v_pk_add_f32 v[146:147], v[146:147], 1.0 op_sel_hi:[1,0]
	v_rcp_f32_e32 v144, v144
	v_rcp_f32_e32 v145, v145
	v_rcp_f32_e32 v146, v146
	v_rcp_f32_e32 v147, v147
	v_pk_mul_f32 v[50:51], v[50:51], v[144:145]
	v_pk_mul_f32 v[52:53], v[52:53], v[146:147]
	v_cvt_pk_bf16_f32 v206, v54, v55
	v_cvt_pk_bf16_f32 v207, v56, v57
	v_cvt_pk_bf16_f32 v208, v50, v51
	v_cvt_pk_bf16_f32 v209, v52, v53
	v_mad_u64_u32 v[144:145], vcc, s30, 8, v[132:133]
	global_store_dwordx4 v[144:145], v[206:209], off offset:256
	s_waitcnt vmcnt(15)
	v_lshlrev_b32_e32 v144, 16, v210
	v_and_b32_e32 v145, 0xffff0000, v210
	v_lshlrev_b32_e32 v146, 16, v211
	v_and_b32_e32 v147, 0xffff0000, v211
	v_mul_f32_e32 v144, 0xbfb8aa3b, v144
	v_mul_f32_e32 v145, 0xbfb8aa3b, v145
	v_mul_f32_e32 v146, 0xbfb8aa3b, v146
	v_mul_f32_e32 v147, 0xbfb8aa3b, v147
	v_exp_f32_e32 v144, v144
	v_exp_f32_e32 v145, v145
	v_exp_f32_e32 v146, v146
	v_exp_f32_e32 v147, v147
	v_pk_add_f32 v[144:145], v[144:145], 1.0 op_sel_hi:[1,0]
	v_pk_add_f32 v[146:147], v[146:147], 1.0 op_sel_hi:[1,0]
	v_rcp_f32_e32 v144, v144
	v_rcp_f32_e32 v145, v145
	v_rcp_f32_e32 v146, v146
	v_rcp_f32_e32 v147, v147
	v_pk_mul_f32 v[46:47], v[46:47], v[144:145]
	v_pk_mul_f32 v[48:49], v[48:49], v[146:147]
	v_lshlrev_b32_e32 v144, 16, v212
	v_and_b32_e32 v145, 0xffff0000, v212
	v_lshlrev_b32_e32 v146, 16, v213
	v_and_b32_e32 v147, 0xffff0000, v213
	v_mul_f32_e32 v144, 0xbfb8aa3b, v144
	v_mul_f32_e32 v145, 0xbfb8aa3b, v145
	v_mul_f32_e32 v146, 0xbfb8aa3b, v146
	v_mul_f32_e32 v147, 0xbfb8aa3b, v147
	v_exp_f32_e32 v144, v144
	v_exp_f32_e32 v145, v145
	v_exp_f32_e32 v146, v146
	v_exp_f32_e32 v147, v147
	v_pk_add_f32 v[144:145], v[144:145], 1.0 op_sel_hi:[1,0]
	v_pk_add_f32 v[146:147], v[146:147], 1.0 op_sel_hi:[1,0]
	v_rcp_f32_e32 v144, v144
	v_rcp_f32_e32 v145, v145
	v_rcp_f32_e32 v146, v146
	v_rcp_f32_e32 v147, v147
	v_pk_mul_f32 v[42:43], v[42:43], v[144:145]
	v_pk_mul_f32 v[44:45], v[44:45], v[146:147]
	v_cvt_pk_bf16_f32 v210, v46, v47
	v_cvt_pk_bf16_f32 v211, v48, v49
	v_cvt_pk_bf16_f32 v212, v42, v43
	v_cvt_pk_bf16_f32 v213, v44, v45
	v_mad_u64_u32 v[144:145], vcc, s30, 9, v[132:133]
	global_store_dwordx4 v[144:145], v[210:213], off
	s_waitcnt vmcnt(15)
; __device__ __forceinline__ unsigned cvt_pk_bf16(float lo, float hi) { f32x2e v = {lo, hi}; bf16x2e b = __builtin_convertvector(v, bf16x2e); return __builtin_bit_cast(unsigned, b); }
; __device__ __forceinline__ float bflo(unsigned w) { return __uint_as_float(w << 16); }
; __device__ __forceinline__ float bfhi(unsigned w) { return __uint_as_float(w & 0xffff0000u); }
; __device__ __forceinline__ float sigm(float x) { return 1.0f / (1.0f + __expf(-x)); }
; __device__ __forceinline__ float bflo(unsigned w) { return __uint_as_float(w << 16); }
; __device__ __forceinline__ float bfhi(unsigned w) { return __uint_as_float(w & 0xffff0000u); }
; __device__ __forceinline__ float sigm(float x) { return 1.0f / (1.0f + __expf(-x)); }
;     __device__ __forceinline__ void operator()(const f32x4 (&acc)[2][2][4][2], const Unit& u, int wr, int wc, int fr, int fq) const {
;     ...
;             for (int m = 0; m < 4; ++m) { const size_t row = (size_t)(row0 + ai * HALF + m * 16);
; #pragma unroll
;                 for (int bj = 0; bj < 2; ++bj) { const f32x4 v0 = acc[ai][bj][m][0], v1 = acc[ai][bj][m][1];
;                     const u32x4 gw = *(const u32x4*)(G + row * ldg + col0 + bj * HALF);
;                     float r[8];
;                     r[0] = sigm(bflo(gw.x)) * v0[0]; r[1] = sigm(bfhi(gw.x)) * v0[1]; r[2] = sigm(bflo(gw.y)) * v0[2]; r[3] = sigm(bfhi(gw.y)) * v0[3];
;                     r[4] = sigm(bflo(gw.z)) * v1[0]; r[5] = sigm(bfhi(gw.z)) * v1[1]; r[6] = sigm(bflo(gw.w)) * v1[2]; r[7] = sigm(bfhi(gw.w)) * v1[3];
;                     bf16_t* op = O + row * ldo + col0 + bj * HALF;
;                     if (!first) { const u32x4 ow = *(const u32x4*)op;
;                         r[0] += bflo(ow.x); r[1] += bfhi(ow.x); r[2] += bflo(ow.y); r[3] += bfhi(ow.y); r[4] += bflo(ow.z); r[5] += bfhi(ow.z); r[6] += bflo(ow.w); r[7] += bfhi(ow.w); }
;                     u32x4 w; w.x = cvt_pk_bf16(r[0], r[1]); w.y = cvt_pk_bf16(r[2], r[3]); w.z = cvt_pk_bf16(r[4], r[5]); w.w = cvt_pk_bf16(r[6], r[7]);
;                     *(u32x4*)op = w; } }
	v_lshlrev_b32_e32 v144, 16, v214
	v_and_b32_e32 v145, 0xffff0000, v214
	v_lshlrev_b32_e32 v146, 16, v215
	v_and_b32_e32 v147, 0xffff0000, v215
	v_mul_f32_e32 v144, 0xbfb8aa3b, v144
	v_mul_f32_e32 v145, 0xbfb8aa3b, v145
	v_mul_f32_e32 v146, 0xbfb8aa3b, v146
	v_mul_f32_e32 v147, 0xbfb8aa3b, v147
	v_exp_f32_e32 v144, v144
	v_exp_f32_e32 v145, v145
	v_exp_f32_e32 v146, v146
	v_exp_f32_e32 v147, v147
	v_pk_add_f32 v[144:145], v[144:145], 1.0 op_sel_hi:[1,0]
	v_pk_add_f32 v[146:147], v[146:147], 1.0 op_sel_hi:[1,0]
	v_rcp_f32_e32 v144, v144
	v_rcp_f32_e32 v145, v145
	v_rcp_f32_e32 v146, v146
	v_rcp_f32_e32 v147, v147
	v_pk_mul_f32 v[38:39], v[38:39], v[144:145]
	v_pk_mul_f32 v[40:41], v[40:41], v[146:147]
	v_lshlrev_b32_e32 v144, 16, v216
	v_and_b32_e32 v145, 0xffff0000, v216
	v_lshlrev_b32_e32 v146, 16, v217
	v_and_b32_e32 v147, 0xffff0000, v217
	v_mul_f32_e32 v144, 0xbfb8aa3b, v144
	v_mul_f32_e32 v145, 0xbfb8aa3b, v145
	v_mul_f32_e32 v146, 0xbfb8aa3b, v146
	v_mul_f32_e32 v147, 0xbfb8aa3b, v147
	v_exp_f32_e32 v144, v144
	v_exp_f32_e32 v145, v145
	v_exp_f32_e32 v146, v146
	v_exp_f32_e32 v147, v147
	v_pk_add_f32 v[144:145], v[144:145], 1.0 op_sel_hi:[1,0]
	v_pk_add_f32 v[146:147], v[146:147], 1.0 op_sel_hi:[1,0]
	v_rcp_f32_e32 v144, v144
	v_rcp_f32_e32 v145, v145
	v_rcp_f32_e32 v146, v146
	v_rcp_f32_e32 v147, v147
	v_pk_mul_f32 v[34:35], v[34:35], v[144:145]
	v_pk_mul_f32 v[36:37], v[36:37], v[146:147]
	v_cvt_pk_bf16_f32 v214, v38, v39
	v_cvt_pk_bf16_f32 v215, v40, v41
	v_cvt_pk_bf16_f32 v216, v34, v35
	v_cvt_pk_bf16_f32 v217, v36, v37
	v_mad_u64_u32 v[144:145], vcc, s30, 9, v[132:133]
	global_store_dwordx4 v[144:145], v[214:217], off offset:256
	s_waitcnt vmcnt(15)
	v_lshlrev_b32_e32 v144, 16, v218
	v_and_b32_e32 v145, 0xffff0000, v218
	v_lshlrev_b32_e32 v146, 16, v219
	v_and_b32_e32 v147, 0xffff0000, v219
	v_mul_f32_e32 v144, 0xbfb8aa3b, v144
	v_mul_f32_e32 v145, 0xbfb8aa3b, v145
	v_mul_f32_e32 v146, 0xbfb8aa3b, v146
	v_mul_f32_e32 v147, 0xbfb8aa3b, v147
	v_exp_f32_e32 v144, v144
	v_exp_f32_e32 v145, v145
	v_exp_f32_e32 v146, v146
	v_exp_f32_e32 v147, v147
	v_pk_add_f32 v[144:145], v[144:145], 1.0 op_sel_hi:[1,0]
	v_pk_add_f32 v[146:147], v[146:147], 1.0 op_sel_hi:[1,0]
	v_rcp_f32_e32 v144, v144
	v_rcp_f32_e32 v145, v145
	v_rcp_f32_e32 v146, v146
	v_rcp_f32_e32 v147, v147
	v_pk_mul_f32 v[30:31], v[30:31], v[144:145]
	v_pk_mul_f32 v[32:33], v[32:33], v[146:147]
	v_lshlrev_b32_e32 v144, 16, v220
	v_and_b32_e32 v145, 0xffff0000, v220
	v_lshlrev_b32_e32 v146, 16, v221
	v_and_b32_e32 v147, 0xffff0000, v221
	v_mul_f32_e32 v144, 0xbfb8aa3b, v144
	v_mul_f32_e32 v145, 0xbfb8aa3b, v145
	v_mul_f32_e32 v146, 0xbfb8aa3b, v146
	v_mul_f32_e32 v147, 0xbfb8aa3b, v147
	v_exp_f32_e32 v144, v144
	v_exp_f32_e32 v145, v145
	v_exp_f32_e32 v146, v146
	v_exp_f32_e32 v147, v147
	v_pk_add_f32 v[144:145], v[144:145], 1.0 op_sel_hi:[1,0]
	v_pk_add_f32 v[146:147], v[146:147], 1.0 op_sel_hi:[1,0]
	v_rcp_f32_e32 v144, v144
	v_rcp_f32_e32 v145, v145
	v_rcp_f32_e32 v146, v146
	v_rcp_f32_e32 v147, v147
	v_pk_mul_f32 v[26:27], v[26:27], v[144:145]
	v_pk_mul_f32 v[28:29], v[28:29], v[146:147]
	v_cvt_pk_bf16_f32 v218, v30, v31
	v_cvt_pk_bf16_f32 v219, v32, v33
	v_cvt_pk_bf16_f32 v220, v26, v27
	v_cvt_pk_bf16_f32 v221, v28, v29
	v_mad_u64_u32 v[144:145], vcc, s30, 10, v[132:133]
	global_store_dwordx4 v[144:145], v[218:221], off
	s_waitcnt vmcnt(15)
	v_lshlrev_b32_e32 v144, 16, v222
	v_and_b32_e32 v145, 0xffff0000, v222
	v_lshlrev_b32_e32 v146, 16, v223
	v_and_b32_e32 v147, 0xffff0000, v223
	v_mul_f32_e32 v144, 0xbfb8aa3b, v144
	v_mul_f32_e32 v145, 0xbfb8aa3b, v145
	v_mul_f32_e32 v146, 0xbfb8aa3b, v146
	v_mul_f32_e32 v147, 0xbfb8aa3b, v147
	v_exp_f32_e32 v144, v144
	v_exp_f32_e32 v145, v145
	v_exp_f32_e32 v146, v146
	v_exp_f32_e32 v147, v147
	v_pk_add_f32 v[144:145], v[144:145], 1.0 op_sel_hi:[1,0]
	v_pk_add_f32 v[146:147], v[146:147], 1.0 op_sel_hi:[1,0]
	v_rcp_f32_e32 v144, v144
	v_rcp_f32_e32 v145, v145
	v_rcp_f32_e32 v146, v146
	v_rcp_f32_e32 v147, v147
	v_pk_mul_f32 v[22:23], v[22:23], v[144:145]
	v_pk_mul_f32 v[24:25], v[24:25], v[146:147]
	v_lshlrev_b32_e32 v144, 16, v224
	v_and_b32_e32 v145, 0xffff0000, v224
	v_lshlrev_b32_e32 v146, 16, v225
	v_and_b32_e32 v147, 0xffff0000, v225
	v_mul_f32_e32 v144, 0xbfb8aa3b, v144
	v_mul_f32_e32 v145, 0xbfb8aa3b, v145
	v_mul_f32_e32 v146, 0xbfb8aa3b, v146
	v_mul_f32_e32 v147, 0xbfb8aa3b, v147
	v_exp_f32_e32 v144, v144
	v_exp_f32_e32 v145, v145
	v_exp_f32_e32 v146, v146
	v_exp_f32_e32 v147, v147
	v_pk_add_f32 v[144:145], v[144:145], 1.0 op_sel_hi:[1,0]
	v_pk_add_f32 v[146:147], v[146:147], 1.0 op_sel_hi:[1,0]
	v_rcp_f32_e32 v144, v144
	v_rcp_f32_e32 v145, v145
	v_rcp_f32_e32 v146, v146
	v_rcp_f32_e32 v147, v147
	v_pk_mul_f32 v[18:19], v[18:19], v[144:145]
	v_pk_mul_f32 v[20:21], v[20:21], v[146:147]
	v_cvt_pk_bf16_f32 v222, v22, v23
	v_cvt_pk_bf16_f32 v223, v24, v25
	v_cvt_pk_bf16_f32 v224, v18, v19
	v_cvt_pk_bf16_f32 v225, v20, v21
	v_mad_u64_u32 v[144:145], vcc, s30, 10, v[132:133]
	global_store_dwordx4 v[144:145], v[222:225], off offset:256
	s_waitcnt vmcnt(15)
; __device__ __forceinline__ unsigned cvt_pk_bf16(float lo, float hi) { f32x2e v = {lo, hi}; bf16x2e b = __builtin_convertvector(v, bf16x2e); return __builtin_bit_cast(unsigned, b); }
; __device__ __forceinline__ float bflo(unsigned w) { return __uint_as_float(w << 16); }
; __device__ __forceinline__ float bfhi(unsigned w) { return __uint_as_float(w & 0xffff0000u); }
; __device__ __forceinline__ float sigm(float x) { return 1.0f / (1.0f + __expf(-x)); }
; __device__ __forceinline__ float bflo(unsigned w) { return __uint_as_float(w << 16); }
; __device__ __forceinline__ float bfhi(unsigned w) { return __uint_as_float(w & 0xffff0000u); }
; __device__ __forceinline__ float sigm(float x) { return 1.0f / (1.0f + __expf(-x)); }
;     __device__ __forceinline__ void operator()(const f32x4 (&acc)[2][2][4][2], const Unit& u, int wr, int wc, int fr, int fq) const {
;     ...
;             for (int m = 0; m < 4; ++m) { const size_t row = (size_t)(row0 + ai * HALF + m * 16);
; #pragma unroll
;                 for (int bj = 0; bj < 2; ++bj) { const f32x4 v0 = acc[ai][bj][m][0], v1 = acc[ai][bj][m][1];
;                     const u32x4 gw = *(const u32x4*)(G + row * ldg + col0 + bj * HALF);
;                     float r[8];
;                     r[0] = sigm(bflo(gw.x)) * v0[0]; r[1] = sigm(bfhi(gw.x)) * v0[1]; r[2] = sigm(bflo(gw.y)) * v0[2]; r[3] = sigm(bfhi(gw.y)) * v0[3];
;                     r[4] = sigm(bflo(gw.z)) * v1[0]; r[5] = sigm(bfhi(gw.z)) * v1[1]; r[6] = sigm(bflo(gw.w)) * v1[2]; r[7] = sigm(bfhi(gw.w)) * v1[3];
;                     bf16_t* op = O + row * ldo + col0 + bj * HALF;
;                     if (!first) { const u32x4 ow = *(const u32x4*)op;
;                         r[0] += bflo(ow.x); r[1] += bfhi(ow.x); r[2] += bflo(ow.y); r[3] += bfhi(ow.y); r[4] += bflo(ow.z); r[5] += bfhi(ow.z); r[6] += bflo(ow.w); r[7] += bfhi(ow.w); }
;                     u32x4 w; w.x = cvt_pk_bf16(r[0], r[1]); w.y = cvt_pk_bf16(r[2], r[3]); w.z = cvt_pk_bf16(r[4], r[5]); w.w = cvt_pk_bf16(r[6], r[7]);
;                     *(u32x4*)op = w; } }
	v_lshlrev_b32_e32 v144, 16, v226
	v_and_b32_e32 v145, 0xffff0000, v226
	v_lshlrev_b32_e32 v146, 16, v227
	v_and_b32_e32 v147, 0xffff0000, v227
	v_mul_f32_e32 v144, 0xbfb8aa3b, v144
	v_mul_f32_e32 v145, 0xbfb8aa3b, v145
	v_mul_f32_e32 v146, 0xbfb8aa3b, v146
	v_mul_f32_e32 v147, 0xbfb8aa3b, v147
	v_exp_f32_e32 v144, v144
	v_exp_f32_e32 v145, v145
	v_exp_f32_e32 v146, v146
	v_exp_f32_e32 v147, v147
	v_pk_add_f32 v[144:145], v[144:145], 1.0 op_sel_hi:[1,0]
	v_pk_add_f32 v[146:147], v[146:147], 1.0 op_sel_hi:[1,0]
	v_rcp_f32_e32 v144, v144
	v_rcp_f32_e32 v145, v145
	v_rcp_f32_e32 v146, v146
	v_rcp_f32_e32 v147, v147
	v_pk_mul_f32 v[14:15], v[14:15], v[144:145]
	v_pk_mul_f32 v[16:17], v[16:17], v[146:147]
	v_lshlrev_b32_e32 v144, 16, v228
	v_and_b32_e32 v145, 0xffff0000, v228
	v_lshlrev_b32_e32 v146, 16, v229
	v_and_b32_e32 v147, 0xffff0000, v229
	v_mul_f32_e32 v144, 0xbfb8aa3b, v144
	v_mul_f32_e32 v145, 0xbfb8aa3b, v145
	v_mul_f32_e32 v146, 0xbfb8aa3b, v146
	v_mul_f32_e32 v147, 0xbfb8aa3b, v147
	v_exp_f32_e32 v144, v144
	v_exp_f32_e32 v145, v145
	v_exp_f32_e32 v146, v146
	v_exp_f32_e32 v147, v147
	v_pk_add_f32 v[144:145], v[144:145], 1.0 op_sel_hi:[1,0]
	v_pk_add_f32 v[146:147], v[146:147], 1.0 op_sel_hi:[1,0]
	v_rcp_f32_e32 v144, v144
	v_rcp_f32_e32 v145, v145
	v_rcp_f32_e32 v146, v146
	v_rcp_f32_e32 v147, v147
	v_pk_mul_f32 v[10:11], v[10:11], v[144:145]
	v_pk_mul_f32 v[12:13], v[12:13], v[146:147]
	v_cvt_pk_bf16_f32 v226, v14, v15
	v_cvt_pk_bf16_f32 v227, v16, v17
	v_cvt_pk_bf16_f32 v228, v10, v11
	v_cvt_pk_bf16_f32 v229, v12, v13
	v_mad_u64_u32 v[144:145], vcc, s30, 11, v[132:133]
	global_store_dwordx4 v[144:145], v[226:229], off
	s_waitcnt vmcnt(15)
	v_lshlrev_b32_e32 v144, 16, v248
	v_and_b32_e32 v145, 0xffff0000, v248
	v_lshlrev_b32_e32 v146, 16, v249
	v_and_b32_e32 v147, 0xffff0000, v249
	v_mul_f32_e32 v144, 0xbfb8aa3b, v144
	v_mul_f32_e32 v145, 0xbfb8aa3b, v145
	v_mul_f32_e32 v146, 0xbfb8aa3b, v146
	v_mul_f32_e32 v147, 0xbfb8aa3b, v147
	v_exp_f32_e32 v144, v144
	v_exp_f32_e32 v145, v145
	v_exp_f32_e32 v146, v146
	v_exp_f32_e32 v147, v147
	v_pk_add_f32 v[144:145], v[144:145], 1.0 op_sel_hi:[1,0]
	v_pk_add_f32 v[146:147], v[146:147], 1.0 op_sel_hi:[1,0]
	v_rcp_f32_e32 v144, v144
	v_rcp_f32_e32 v145, v145
	v_rcp_f32_e32 v146, v146
	v_rcp_f32_e32 v147, v147
	v_pk_mul_f32 v[6:7], v[6:7], v[144:145]
	v_pk_mul_f32 v[8:9], v[8:9], v[146:147]
	v_lshlrev_b32_e32 v144, 16, v250
	v_and_b32_e32 v145, 0xffff0000, v250
	v_lshlrev_b32_e32 v146, 16, v251
	v_and_b32_e32 v147, 0xffff0000, v251
	v_mul_f32_e32 v144, 0xbfb8aa3b, v144
	v_mul_f32_e32 v145, 0xbfb8aa3b, v145
	v_mul_f32_e32 v146, 0xbfb8aa3b, v146
	v_mul_f32_e32 v147, 0xbfb8aa3b, v147
	v_exp_f32_e32 v144, v144
	v_exp_f32_e32 v145, v145
	v_exp_f32_e32 v146, v146
	v_exp_f32_e32 v147, v147
	v_pk_add_f32 v[144:145], v[144:145], 1.0 op_sel_hi:[1,0]
	v_pk_add_f32 v[146:147], v[146:147], 1.0 op_sel_hi:[1,0]
	v_rcp_f32_e32 v144, v144
	v_rcp_f32_e32 v145, v145
	v_rcp_f32_e32 v146, v146
	v_rcp_f32_e32 v147, v147
	v_pk_mul_f32 v[2:3], v[2:3], v[144:145]
	v_pk_mul_f32 v[4:5], v[4:5], v[146:147]
	v_cvt_pk_bf16_f32 v248, v6, v7
	v_cvt_pk_bf16_f32 v249, v8, v9
	v_cvt_pk_bf16_f32 v250, v2, v3
	v_cvt_pk_bf16_f32 v251, v4, v5
	v_mad_u64_u32 v[144:145], vcc, s30, 11, v[132:133]
	global_store_dwordx4 v[144:145], v[248:251], off offset:256
.Lg5_epi_done:
	s_andn2_b64 vcc, exec, s[6:7]
	s_mov_b64 s[6:7], -1
	s_cbranch_vccnz .LBB0_1125
	s_andn2_b64 vcc, exec, s[12:13]
	s_cbranch_vccnz .LBB0_1124
	s_barrier
	s_branch .LBB0_1124
